# K-loops: s_setprio 1 raised before the barrier opening each MFMA block, lowered after the closing barrier; mid-block prio flips and redundant lgkmcnt(0) removed; on top of P0 item pipeline
# speedup vs baseline: 1.0088x; 1.0088x over previous
.LBB0_446:
	ds_read_b128 v[148:151], v165
	ds_read_b128 v[174:177], v165 offset:1024
	ds_read_b128 v[180:183], v165 offset:2048
	ds_read_b128 v[184:187], v165 offset:3072
	ds_read_b128 v[188:191], v169
	ds_read_b128 v[192:195], v169 offset:1024
	ds_read_b128 v[196:199], v169 offset:2048
	ds_read_b128 v[200:203], v169 offset:3072
	s_add_u32 s50, s4, 0xfff00080
	s_addc_u32 s51, s5, -1
	s_cmp_eq_u32 s68, 60
	s_cselect_b32 s53, s3, s51
	s_cselect_b32 s52, s8, s50
	s_cselect_b32 s51, s39, s65
	s_cselect_b32 s50, s45, s63
	v_lshl_add_u64 v[154:155], s[4:5], 0, v[140:141]
	s_add_i32 m0, s7, 0xc000
	ds_read_b128 v[204:207], v173
	ds_read_b128 v[208:211], v173 offset:1024
	ds_read_b128 v[212:215], v173 offset:2048
	ds_read_b128 v[216:219], v173 offset:3072
	ds_read_b128 v[220:223], v173 offset:4096
	ds_read_b128 v[224:227], v173 offset:5120
	ds_read_b128 v[228:231], v173 offset:6144
	ds_read_b128 v[236:239], v173 offset:7168
	global_load_lds_dwordx4 v[154:155], off
	v_lshl_add_u64 v[154:155], s[4:5], 0, v[142:143]
	s_add_i32 m0, s7, 0xe000
	s_nop 0
	global_load_lds_dwordx4 v[154:155], off
	s_waitcnt vmcnt(8)
	s_waitcnt lgkmcnt(0)
	s_setprio 1
	s_barrier
	v_mfma_f32_16x16x32_bf16 v[126:129], v[148:151], v[204:207], v[126:129]
	v_mfma_f32_16x16x32_bf16 v[122:125], v[180:183], v[204:207], v[122:125]
	v_mfma_f32_16x16x32_bf16 v[110:113], v[148:151], v[212:215], v[110:113]
	v_mfma_f32_16x16x32_bf16 v[106:109], v[180:183], v[212:215], v[106:109]
	v_mfma_f32_16x16x32_bf16 v[94:97], v[148:151], v[220:223], v[94:97]
	v_mfma_f32_16x16x32_bf16 v[90:93], v[180:183], v[220:223], v[90:93]
	v_mfma_f32_16x16x32_bf16 v[78:81], v[148:151], v[228:231], v[78:81]
	v_mfma_f32_16x16x32_bf16 v[74:77], v[180:183], v[228:231], v[74:77]
	v_mfma_f32_16x16x32_bf16 v[126:129], v[174:177], v[208:211], v[126:129]
	v_mfma_f32_16x16x32_bf16 v[122:125], v[184:187], v[208:211], v[122:125]
	v_mfma_f32_16x16x32_bf16 v[110:113], v[174:177], v[216:219], v[110:113]
	v_mfma_f32_16x16x32_bf16 v[106:109], v[184:187], v[216:219], v[106:109]
	v_mfma_f32_16x16x32_bf16 v[94:97], v[174:177], v[224:227], v[94:97]
	v_mfma_f32_16x16x32_bf16 v[90:93], v[184:187], v[224:227], v[90:93]
	v_mfma_f32_16x16x32_bf16 v[78:81], v[174:177], v[236:239], v[78:81]
	v_mfma_f32_16x16x32_bf16 v[74:77], v[184:187], v[236:239], v[74:77]
	v_mfma_f32_16x16x32_bf16 v[118:121], v[188:191], v[204:207], v[118:121]
	v_mfma_f32_16x16x32_bf16 v[114:117], v[196:199], v[204:207], v[114:117]
	v_mfma_f32_16x16x32_bf16 v[102:105], v[188:191], v[212:215], v[102:105]
	v_mfma_f32_16x16x32_bf16 v[98:101], v[196:199], v[212:215], v[98:101]
	v_mfma_f32_16x16x32_bf16 v[86:89], v[188:191], v[220:223], v[86:89]
	v_mfma_f32_16x16x32_bf16 v[82:85], v[196:199], v[220:223], v[82:85]
	v_mfma_f32_16x16x32_bf16 v[70:73], v[188:191], v[228:231], v[70:73]
	v_mfma_f32_16x16x32_bf16 v[66:69], v[196:199], v[228:231], v[66:69]
	v_mfma_f32_16x16x32_bf16 v[118:121], v[192:195], v[208:211], v[118:121]
	v_mfma_f32_16x16x32_bf16 v[114:117], v[200:203], v[208:211], v[114:117]
	v_mfma_f32_16x16x32_bf16 v[102:105], v[192:195], v[216:219], v[102:105]
	v_mfma_f32_16x16x32_bf16 v[98:101], v[200:203], v[216:219], v[98:101]
	v_mfma_f32_16x16x32_bf16 v[86:89], v[192:195], v[224:227], v[86:89]
	v_mfma_f32_16x16x32_bf16 v[82:85], v[200:203], v[224:227], v[82:85]
	v_mfma_f32_16x16x32_bf16 v[70:73], v[192:195], v[236:239], v[70:73]
	v_mfma_f32_16x16x32_bf16 v[66:69], v[200:203], v[236:239], v[66:69]
	s_barrier
	s_setprio 0
	s_add_i32 s69, s59, s35
	v_lshl_add_u64 v[154:155], s[50:51], 0, v[132:133]
	s_mov_b32 m0, s69
	ds_read_b128 v[204:207], v173 offset:16384
	ds_read_b128 v[208:211], v173 offset:17408
	ds_read_b128 v[212:215], v173 offset:18432
	ds_read_b128 v[216:219], v173 offset:19456
	ds_read_b128 v[220:223], v173 offset:20480
	ds_read_b128 v[224:227], v173 offset:21504
	ds_read_b128 v[228:231], v173 offset:22528
	ds_read_b128 v[236:239], v173 offset:23552
	global_load_lds_dwordx4 v[154:155], off
	s_add_i32 m0, s69, 0x2000
	s_add_u32 s70, s50, 0x100000
	v_lshl_add_u64 v[158:159], s[50:51], 0, v[136:137]
	s_addc_u32 s71, s51, 0
	s_add_i32 s69, s60, s35
	global_load_lds_dwordx4 v[158:159], off
	v_lshl_add_u64 v[162:163], s[70:71], 0, v[132:133]
	s_mov_b32 m0, s69
	v_lshl_add_u64 v[166:167], s[52:53], 0, v[134:135]
	global_load_lds_dwordx4 v[162:163], off
	v_lshl_add_u64 v[162:163], s[70:71], 0, v[136:137]
	s_add_i32 m0, s69, 0x2000
	s_nop 0
	global_load_lds_dwordx4 v[162:163], off
	v_lshl_add_u64 v[162:163], s[52:53], 0, v[130:131]
	s_mov_b32 m0, s7
	s_nop 0
	global_load_lds_dwordx4 v[162:163], off
	s_mov_b32 m0, s37
	s_nop 0
	global_load_lds_dwordx4 v[166:167], off
	s_waitcnt vmcnt(8)
	s_waitcnt lgkmcnt(0)
	s_setprio 1
	s_barrier
	v_mfma_f32_16x16x32_bf16 v[62:65], v[148:151], v[204:207], v[62:65]
	v_mfma_f32_16x16x32_bf16 v[58:61], v[180:183], v[204:207], v[58:61]
	v_mfma_f32_16x16x32_bf16 v[46:49], v[148:151], v[212:215], v[46:49]
	v_mfma_f32_16x16x32_bf16 v[42:45], v[180:183], v[212:215], v[42:45]
	v_mfma_f32_16x16x32_bf16 v[30:33], v[148:151], v[220:223], v[30:33]
	v_mfma_f32_16x16x32_bf16 v[26:29], v[180:183], v[220:223], v[26:29]
	v_mfma_f32_16x16x32_bf16 v[14:17], v[148:151], v[228:231], v[14:17]
	v_mfma_f32_16x16x32_bf16 v[10:13], v[180:183], v[228:231], v[10:13]
	v_mfma_f32_16x16x32_bf16 v[62:65], v[174:177], v[208:211], v[62:65]
	v_mfma_f32_16x16x32_bf16 v[58:61], v[184:187], v[208:211], v[58:61]
	v_mfma_f32_16x16x32_bf16 v[46:49], v[174:177], v[216:219], v[46:49]
	v_mfma_f32_16x16x32_bf16 v[42:45], v[184:187], v[216:219], v[42:45]
	v_mfma_f32_16x16x32_bf16 v[30:33], v[174:177], v[224:227], v[30:33]
	v_mfma_f32_16x16x32_bf16 v[26:29], v[184:187], v[224:227], v[26:29]
	v_mfma_f32_16x16x32_bf16 v[14:17], v[174:177], v[236:239], v[14:17]
	v_mfma_f32_16x16x32_bf16 v[10:13], v[184:187], v[236:239], v[10:13]
	v_mfma_f32_16x16x32_bf16 v[54:57], v[188:191], v[204:207], v[54:57]
	v_mfma_f32_16x16x32_bf16 v[50:53], v[196:199], v[204:207], v[50:53]
	v_mfma_f32_16x16x32_bf16 v[38:41], v[188:191], v[212:215], v[38:41]
	v_mfma_f32_16x16x32_bf16 v[34:37], v[196:199], v[212:215], v[34:37]
	v_mfma_f32_16x16x32_bf16 v[22:25], v[188:191], v[220:223], v[22:25]
	v_mfma_f32_16x16x32_bf16 v[18:21], v[196:199], v[220:223], v[18:21]
	v_mfma_f32_16x16x32_bf16 v[6:9], v[188:191], v[228:231], v[6:9]
	v_mfma_f32_16x16x32_bf16 v[2:5], v[196:199], v[228:231], v[2:5]
	v_mfma_f32_16x16x32_bf16 v[54:57], v[192:195], v[208:211], v[54:57]
	v_mfma_f32_16x16x32_bf16 v[50:53], v[200:203], v[208:211], v[50:53]
	v_mfma_f32_16x16x32_bf16 v[38:41], v[192:195], v[216:219], v[38:41]
	v_mfma_f32_16x16x32_bf16 v[34:37], v[200:203], v[216:219], v[34:37]
	v_mfma_f32_16x16x32_bf16 v[22:25], v[192:195], v[224:227], v[22:25]
	v_mfma_f32_16x16x32_bf16 v[18:21], v[200:203], v[224:227], v[18:21]
	v_mfma_f32_16x16x32_bf16 v[6:9], v[192:195], v[236:239], v[6:9]
	v_mfma_f32_16x16x32_bf16 v[2:5], v[200:203], v[236:239], v[2:5]
	s_barrier
	s_setprio 0
	s_add_i32 s69, 0, 0x18000
	v_add_u32_e32 v139, s69, v161
	s_add_i32 s70, 0, 0x1c000
	ds_read_b128 v[148:151], v139
	ds_read_b128 v[174:177], v139 offset:1024
	ds_read_b128 v[180:183], v139 offset:2048
	ds_read_b128 v[184:187], v139 offset:3072
	v_add_u32_e32 v139, s70, v161
	ds_read_b128 v[188:191], v139
	ds_read_b128 v[192:195], v139 offset:1024
	ds_read_b128 v[196:199], v139 offset:2048
	ds_read_b128 v[200:203], v139 offset:3072
	s_add_u32 s52, s52, 0x100000
	s_addc_u32 s53, s53, 0
	s_mov_b32 m0, s41
	v_lshl_add_u64 v[170:171], s[52:53], 0, v[130:131]
	ds_read_b128 v[204:207], v173 offset:32768
	ds_read_b128 v[208:211], v173 offset:33792
	ds_read_b128 v[212:215], v173 offset:34816
	ds_read_b128 v[216:219], v173 offset:35840
	ds_read_b128 v[220:223], v173 offset:36864
	ds_read_b128 v[224:227], v173 offset:37888
	ds_read_b128 v[228:231], v173 offset:38912
	ds_read_b128 v[236:239], v173 offset:39936
	global_load_lds_dwordx4 v[170:171], off
	v_lshl_add_u64 v[170:171], s[52:53], 0, v[134:135]
	s_mov_b32 m0, s43
	s_nop 0
	global_load_lds_dwordx4 v[170:171], off
	s_waitcnt vmcnt(8)
	s_waitcnt lgkmcnt(0)
	s_setprio 1
	s_barrier
	v_mfma_f32_16x16x32_bf16 v[126:129], v[148:151], v[204:207], v[126:129]
	v_mfma_f32_16x16x32_bf16 v[122:125], v[180:183], v[204:207], v[122:125]
	v_mfma_f32_16x16x32_bf16 v[110:113], v[148:151], v[212:215], v[110:113]
	v_mfma_f32_16x16x32_bf16 v[106:109], v[180:183], v[212:215], v[106:109]
	v_mfma_f32_16x16x32_bf16 v[94:97], v[148:151], v[220:223], v[94:97]
	v_mfma_f32_16x16x32_bf16 v[90:93], v[180:183], v[220:223], v[90:93]
	v_mfma_f32_16x16x32_bf16 v[78:81], v[148:151], v[228:231], v[78:81]
	v_mfma_f32_16x16x32_bf16 v[74:77], v[180:183], v[228:231], v[74:77]
	v_mfma_f32_16x16x32_bf16 v[126:129], v[174:177], v[208:211], v[126:129]
	v_mfma_f32_16x16x32_bf16 v[122:125], v[184:187], v[208:211], v[122:125]
	v_mfma_f32_16x16x32_bf16 v[110:113], v[174:177], v[216:219], v[110:113]
	v_mfma_f32_16x16x32_bf16 v[106:109], v[184:187], v[216:219], v[106:109]
	v_mfma_f32_16x16x32_bf16 v[94:97], v[174:177], v[224:227], v[94:97]
	v_mfma_f32_16x16x32_bf16 v[90:93], v[184:187], v[224:227], v[90:93]
	v_mfma_f32_16x16x32_bf16 v[78:81], v[174:177], v[236:239], v[78:81]
	v_mfma_f32_16x16x32_bf16 v[74:77], v[184:187], v[236:239], v[74:77]
	v_mfma_f32_16x16x32_bf16 v[118:121], v[188:191], v[204:207], v[118:121]
	v_mfma_f32_16x16x32_bf16 v[114:117], v[196:199], v[204:207], v[114:117]
	v_mfma_f32_16x16x32_bf16 v[102:105], v[188:191], v[212:215], v[102:105]
	v_mfma_f32_16x16x32_bf16 v[98:101], v[196:199], v[212:215], v[98:101]
	v_mfma_f32_16x16x32_bf16 v[86:89], v[188:191], v[220:223], v[86:89]
	v_mfma_f32_16x16x32_bf16 v[82:85], v[196:199], v[220:223], v[82:85]
	v_mfma_f32_16x16x32_bf16 v[70:73], v[188:191], v[228:231], v[70:73]
	v_mfma_f32_16x16x32_bf16 v[66:69], v[196:199], v[228:231], v[66:69]
	v_mfma_f32_16x16x32_bf16 v[118:121], v[192:195], v[208:211], v[118:121]
	v_mfma_f32_16x16x32_bf16 v[114:117], v[200:203], v[208:211], v[114:117]
	v_mfma_f32_16x16x32_bf16 v[102:105], v[192:195], v[216:219], v[102:105]
	v_mfma_f32_16x16x32_bf16 v[98:101], v[200:203], v[216:219], v[98:101]
	v_mfma_f32_16x16x32_bf16 v[86:89], v[192:195], v[224:227], v[86:89]
	v_mfma_f32_16x16x32_bf16 v[82:85], v[200:203], v[224:227], v[82:85]
	v_mfma_f32_16x16x32_bf16 v[70:73], v[192:195], v[236:239], v[70:73]
	v_mfma_f32_16x16x32_bf16 v[66:69], v[200:203], v[236:239], v[66:69]
	s_barrier
	s_setprio 0
	s_add_i32 s52, s69, s35
	v_lshl_add_u64 v[154:155], v[154:155], 0, s[16:17]
	s_mov_b32 m0, s52
	ds_read_b128 v[204:207], v173 offset:49152
	ds_read_b128 v[208:211], v173 offset:50176
	ds_read_b128 v[212:215], v173 offset:51200
	ds_read_b128 v[216:219], v173 offset:52224
	ds_read_b128 v[220:223], v173 offset:53248
	ds_read_b128 v[224:227], v173 offset:54272
	ds_read_b128 v[228:231], v173 offset:55296
	ds_read_b128 v[236:239], v173 offset:56320
	global_load_lds_dwordx4 v[154:155], off
	s_add_i32 m0, s52, 0x2000
	s_add_u32 s50, s50, 0x100080
	v_lshl_add_u64 v[154:155], v[158:159], 0, s[16:17]
	s_addc_u32 s51, s51, 0
	s_add_i32 s52, s70, s35
	global_load_lds_dwordx4 v[154:155], off
	v_lshl_add_u64 v[154:155], s[50:51], 0, v[132:133]
	s_mov_b32 m0, s52
	s_nop 0
	global_load_lds_dwordx4 v[154:155], off
	v_lshl_add_u64 v[154:155], s[50:51], 0, v[136:137]
	s_add_i32 m0, s52, 0x2000
	s_nop 0
	global_load_lds_dwordx4 v[154:155], off
	v_lshl_add_u64 v[154:155], v[162:163], 0, s[16:17]
	s_mov_b32 m0, s57
	s_nop 0
	global_load_lds_dwordx4 v[154:155], off
	v_lshl_add_u64 v[154:155], v[166:167], 0, s[16:17]
	s_mov_b32 m0, s58
	s_nop 0
	global_load_lds_dwordx4 v[154:155], off
	s_waitcnt vmcnt(8)
	s_waitcnt lgkmcnt(0)
	s_setprio 1
	s_barrier
	v_mfma_f32_16x16x32_bf16 v[62:65], v[148:151], v[204:207], v[62:65]
	v_mfma_f32_16x16x32_bf16 v[58:61], v[180:183], v[204:207], v[58:61]
	v_mfma_f32_16x16x32_bf16 v[46:49], v[148:151], v[212:215], v[46:49]
	v_mfma_f32_16x16x32_bf16 v[42:45], v[180:183], v[212:215], v[42:45]
	v_mfma_f32_16x16x32_bf16 v[30:33], v[148:151], v[220:223], v[30:33]
	v_mfma_f32_16x16x32_bf16 v[26:29], v[180:183], v[220:223], v[26:29]
	v_mfma_f32_16x16x32_bf16 v[14:17], v[148:151], v[228:231], v[14:17]
	v_mfma_f32_16x16x32_bf16 v[10:13], v[180:183], v[228:231], v[10:13]
	v_mfma_f32_16x16x32_bf16 v[62:65], v[174:177], v[208:211], v[62:65]
	v_mfma_f32_16x16x32_bf16 v[58:61], v[184:187], v[208:211], v[58:61]
	v_mfma_f32_16x16x32_bf16 v[46:49], v[174:177], v[216:219], v[46:49]
	v_mfma_f32_16x16x32_bf16 v[42:45], v[184:187], v[216:219], v[42:45]
	v_mfma_f32_16x16x32_bf16 v[30:33], v[174:177], v[224:227], v[30:33]
	v_mfma_f32_16x16x32_bf16 v[26:29], v[184:187], v[224:227], v[26:29]
	v_mfma_f32_16x16x32_bf16 v[14:17], v[174:177], v[236:239], v[14:17]
	v_mfma_f32_16x16x32_bf16 v[10:13], v[184:187], v[236:239], v[10:13]
	v_mfma_f32_16x16x32_bf16 v[54:57], v[188:191], v[204:207], v[54:57]
	v_mfma_f32_16x16x32_bf16 v[50:53], v[196:199], v[204:207], v[50:53]
	v_mfma_f32_16x16x32_bf16 v[38:41], v[188:191], v[212:215], v[38:41]
	v_mfma_f32_16x16x32_bf16 v[34:37], v[196:199], v[212:215], v[34:37]
	v_mfma_f32_16x16x32_bf16 v[22:25], v[188:191], v[220:223], v[22:25]
	v_mfma_f32_16x16x32_bf16 v[18:21], v[196:199], v[220:223], v[18:21]
	v_mfma_f32_16x16x32_bf16 v[6:9], v[188:191], v[228:231], v[6:9]
	v_mfma_f32_16x16x32_bf16 v[2:5], v[196:199], v[228:231], v[2:5]
	v_mfma_f32_16x16x32_bf16 v[54:57], v[192:195], v[208:211], v[54:57]
	v_mfma_f32_16x16x32_bf16 v[50:53], v[200:203], v[208:211], v[50:53]
	v_mfma_f32_16x16x32_bf16 v[38:41], v[192:195], v[216:219], v[38:41]
	v_mfma_f32_16x16x32_bf16 v[34:37], v[200:203], v[216:219], v[34:37]
	v_mfma_f32_16x16x32_bf16 v[22:25], v[192:195], v[224:227], v[22:25]
	v_mfma_f32_16x16x32_bf16 v[18:21], v[200:203], v[224:227], v[18:21]
	v_mfma_f32_16x16x32_bf16 v[6:9], v[192:195], v[236:239], v[6:9]
	v_mfma_f32_16x16x32_bf16 v[2:5], v[200:203], v[236:239], v[2:5]
	s_barrier
	s_setprio 0
	s_add_i32 s68, s68, 2
	s_add_u32 s4, s4, 0x100
	s_addc_u32 s5, s5, 0
	s_add_u32 s63, s63, 0x100
	s_addc_u32 s65, s65, 0
	s_cmp_gt_u32 s68, 61
	s_cbranch_scc0 .LBB0_446
	s_and_b64 vcc, exec, s[20:21]
	s_cbranch_vccz .LBB0_449
	s_barrier

.LBB0_668:
	ds_read_b128 v[154:157], v151
	ds_read_b128 v[158:161], v151 offset:1024
	ds_read_b128 v[162:165], v151 offset:2048
	ds_read_b128 v[166:169], v151 offset:3072
	ds_read_b128 v[170:173], v152
	ds_read_b128 v[174:177], v152 offset:1024
	ds_read_b128 v[178:181], v152 offset:2048
	ds_read_b128 v[182:185], v152 offset:3072
	s_add_u32 s36, s34, 0xfff00080
	s_addc_u32 s37, s35, -1
	s_cmp_eq_u32 s68, 60
	s_cselect_b32 s39, s25, s37
	s_cselect_b32 s38, s61, s36
	s_cselect_b32 s37, s23, s65
	s_cselect_b32 s36, s62, s63
	v_lshl_add_u64 v[148:149], s[34:35], 0, v[140:141]
	s_add_i32 m0, s31, 0xc000
	ds_read_b128 v[186:189], v153
	ds_read_b128 v[190:193], v153 offset:1024
	ds_read_b128 v[194:197], v153 offset:2048
	ds_read_b128 v[198:201], v153 offset:3072
	ds_read_b128 v[202:205], v153 offset:4096
	ds_read_b128 v[206:209], v153 offset:5120
	ds_read_b128 v[210:213], v153 offset:6144
	ds_read_b128 v[214:217], v153 offset:7168
	global_load_lds_dwordx4 v[148:149], off
	v_lshl_add_u64 v[148:149], s[34:35], 0, v[142:143]
	s_add_i32 m0, s31, 0xe000
	s_nop 0
	global_load_lds_dwordx4 v[148:149], off
	s_waitcnt vmcnt(8)
	s_waitcnt lgkmcnt(0)
	s_setprio 1
	s_barrier
	v_mfma_f32_16x16x32_bf16 v[126:129], v[154:157], v[186:189], v[126:129]
	v_mfma_f32_16x16x32_bf16 v[122:125], v[162:165], v[186:189], v[122:125]
	v_mfma_f32_16x16x32_bf16 v[114:117], v[154:157], v[194:197], v[114:117]
	v_mfma_f32_16x16x32_bf16 v[106:109], v[162:165], v[194:197], v[106:109]
	v_mfma_f32_16x16x32_bf16 v[98:101], v[154:157], v[202:205], v[98:101]
	v_mfma_f32_16x16x32_bf16 v[90:93], v[162:165], v[202:205], v[90:93]
	v_mfma_f32_16x16x32_bf16 v[82:85], v[154:157], v[210:213], v[82:85]
	v_mfma_f32_16x16x32_bf16 v[74:77], v[162:165], v[210:213], v[74:77]
	v_mfma_f32_16x16x32_bf16 v[126:129], v[158:161], v[190:193], v[126:129]
	v_mfma_f32_16x16x32_bf16 v[122:125], v[166:169], v[190:193], v[122:125]
	v_mfma_f32_16x16x32_bf16 v[114:117], v[158:161], v[198:201], v[114:117]
	v_mfma_f32_16x16x32_bf16 v[106:109], v[166:169], v[198:201], v[106:109]
	v_mfma_f32_16x16x32_bf16 v[98:101], v[158:161], v[206:209], v[98:101]
	v_mfma_f32_16x16x32_bf16 v[90:93], v[166:169], v[206:209], v[90:93]
	v_mfma_f32_16x16x32_bf16 v[82:85], v[158:161], v[214:217], v[82:85]
	v_mfma_f32_16x16x32_bf16 v[74:77], v[166:169], v[214:217], v[74:77]
	v_mfma_f32_16x16x32_bf16 v[118:121], v[170:173], v[186:189], v[118:121]
	v_mfma_f32_16x16x32_bf16 v[110:113], v[178:181], v[186:189], v[110:113]
	v_mfma_f32_16x16x32_bf16 v[102:105], v[170:173], v[194:197], v[102:105]
	v_mfma_f32_16x16x32_bf16 v[94:97], v[178:181], v[194:197], v[94:97]
	v_mfma_f32_16x16x32_bf16 v[86:89], v[170:173], v[202:205], v[86:89]
	v_mfma_f32_16x16x32_bf16 v[78:81], v[178:181], v[202:205], v[78:81]
	v_mfma_f32_16x16x32_bf16 v[70:73], v[170:173], v[210:213], v[70:73]
	v_mfma_f32_16x16x32_bf16 v[66:69], v[178:181], v[210:213], v[66:69]
	v_mfma_f32_16x16x32_bf16 v[118:121], v[174:177], v[190:193], v[118:121]
	v_mfma_f32_16x16x32_bf16 v[110:113], v[182:185], v[190:193], v[110:113]
	v_mfma_f32_16x16x32_bf16 v[102:105], v[174:177], v[198:201], v[102:105]
	v_mfma_f32_16x16x32_bf16 v[94:97], v[182:185], v[198:201], v[94:97]
	v_mfma_f32_16x16x32_bf16 v[86:89], v[174:177], v[206:209], v[86:89]
	v_mfma_f32_16x16x32_bf16 v[78:81], v[182:185], v[206:209], v[78:81]
	v_mfma_f32_16x16x32_bf16 v[70:73], v[174:177], v[214:217], v[70:73]
	v_mfma_f32_16x16x32_bf16 v[66:69], v[182:185], v[214:217], v[66:69]
	s_barrier
	s_setprio 0
	s_add_i32 s69, s54, s47
	v_lshl_add_u64 v[148:149], s[36:37], 0, v[136:137]
	s_mov_b32 m0, s69
	ds_read_b128 v[186:189], v153 offset:16384
	ds_read_b128 v[190:193], v153 offset:17408
	ds_read_b128 v[194:197], v153 offset:18432
	ds_read_b128 v[198:201], v153 offset:19456
	ds_read_b128 v[202:205], v153 offset:20480
	ds_read_b128 v[206:209], v153 offset:21504
	ds_read_b128 v[210:213], v153 offset:22528
	ds_read_b128 v[214:217], v153 offset:23552
	global_load_lds_dwordx4 v[148:149], off
	s_add_i32 m0, s69, 0x2000
	s_add_u32 s70, s36, 0x100000
	v_lshl_add_u64 v[218:219], s[36:37], 0, v[132:133]
	s_addc_u32 s71, s37, 0
	s_add_i32 s69, s55, s47
	global_load_lds_dwordx4 v[218:219], off
	v_lshl_add_u64 v[220:221], s[70:71], 0, v[136:137]
	s_mov_b32 m0, s69
	v_lshl_add_u64 v[222:223], s[38:39], 0, v[134:135]
	global_load_lds_dwordx4 v[220:221], off
	v_lshl_add_u64 v[220:221], s[70:71], 0, v[132:133]
	s_add_i32 m0, s69, 0x2000
	s_nop 0
	global_load_lds_dwordx4 v[220:221], off
	v_lshl_add_u64 v[220:221], s[38:39], 0, v[138:139]
	s_mov_b32 m0, s31
	s_nop 0
	global_load_lds_dwordx4 v[220:221], off
	s_mov_b32 m0, s48
	s_nop 0
	global_load_lds_dwordx4 v[222:223], off
	s_waitcnt vmcnt(8)
	s_waitcnt lgkmcnt(0)
	s_setprio 1
	s_barrier
	v_mfma_f32_16x16x32_bf16 v[62:65], v[154:157], v[186:189], v[62:65]
	v_mfma_f32_16x16x32_bf16 v[58:61], v[162:165], v[186:189], v[58:61]
	v_mfma_f32_16x16x32_bf16 v[50:53], v[154:157], v[194:197], v[50:53]
	v_mfma_f32_16x16x32_bf16 v[42:45], v[162:165], v[194:197], v[42:45]
	v_mfma_f32_16x16x32_bf16 v[34:37], v[154:157], v[202:205], v[34:37]
	v_mfma_f32_16x16x32_bf16 v[26:29], v[162:165], v[202:205], v[26:29]
	v_mfma_f32_16x16x32_bf16 v[18:21], v[154:157], v[210:213], v[18:21]
	v_mfma_f32_16x16x32_bf16 v[10:13], v[162:165], v[210:213], v[10:13]
	v_mfma_f32_16x16x32_bf16 v[62:65], v[158:161], v[190:193], v[62:65]
	v_mfma_f32_16x16x32_bf16 v[58:61], v[166:169], v[190:193], v[58:61]
	v_mfma_f32_16x16x32_bf16 v[50:53], v[158:161], v[198:201], v[50:53]
	v_mfma_f32_16x16x32_bf16 v[42:45], v[166:169], v[198:201], v[42:45]
	v_mfma_f32_16x16x32_bf16 v[34:37], v[158:161], v[206:209], v[34:37]
	v_mfma_f32_16x16x32_bf16 v[26:29], v[166:169], v[206:209], v[26:29]
	v_mfma_f32_16x16x32_bf16 v[18:21], v[158:161], v[214:217], v[18:21]
	v_mfma_f32_16x16x32_bf16 v[10:13], v[166:169], v[214:217], v[10:13]
	v_mfma_f32_16x16x32_bf16 v[54:57], v[170:173], v[186:189], v[54:57]
	v_mfma_f32_16x16x32_bf16 v[46:49], v[178:181], v[186:189], v[46:49]
	v_mfma_f32_16x16x32_bf16 v[38:41], v[170:173], v[194:197], v[38:41]
	v_mfma_f32_16x16x32_bf16 v[30:33], v[178:181], v[194:197], v[30:33]
	v_mfma_f32_16x16x32_bf16 v[22:25], v[170:173], v[202:205], v[22:25]
	v_mfma_f32_16x16x32_bf16 v[14:17], v[178:181], v[202:205], v[14:17]
	v_mfma_f32_16x16x32_bf16 v[6:9], v[170:173], v[210:213], v[6:9]
	v_mfma_f32_16x16x32_bf16 v[2:5], v[178:181], v[210:213], v[2:5]
	v_mfma_f32_16x16x32_bf16 v[54:57], v[174:177], v[190:193], v[54:57]
	v_mfma_f32_16x16x32_bf16 v[46:49], v[182:185], v[190:193], v[46:49]
	v_mfma_f32_16x16x32_bf16 v[38:41], v[174:177], v[198:201], v[38:41]
	v_mfma_f32_16x16x32_bf16 v[30:33], v[182:185], v[198:201], v[30:33]
	v_mfma_f32_16x16x32_bf16 v[22:25], v[174:177], v[206:209], v[22:25]
	v_mfma_f32_16x16x32_bf16 v[14:17], v[182:185], v[206:209], v[14:17]
	v_mfma_f32_16x16x32_bf16 v[6:9], v[174:177], v[214:217], v[6:9]
	v_mfma_f32_16x16x32_bf16 v[2:5], v[182:185], v[214:217], v[2:5]
	s_barrier
	s_setprio 0
	s_add_i32 s69, 0, 0x18000
	s_add_i32 s70, 0, 0x1c000
	v_add_u32_e32 v166, s69, v131
	v_add_u32_e32 v182, s70, v131
	ds_read_b128 v[154:157], v166
	ds_read_b128 v[158:161], v166 offset:1024
	ds_read_b128 v[162:165], v166 offset:2048
	ds_read_b128 v[166:169], v166 offset:3072
	ds_read_b128 v[170:173], v182
	ds_read_b128 v[174:177], v182 offset:1024
	ds_read_b128 v[178:181], v182 offset:2048
	ds_read_b128 v[182:185], v182 offset:3072
	s_add_u32 s38, s38, 0x100000
	s_addc_u32 s39, s39, 0
	s_mov_b32 m0, s49
	v_lshl_add_u64 v[224:225], s[38:39], 0, v[138:139]
	ds_read_b128 v[186:189], v153 offset:32768
	ds_read_b128 v[190:193], v153 offset:33792
	ds_read_b128 v[194:197], v153 offset:34816
	ds_read_b128 v[198:201], v153 offset:35840
	ds_read_b128 v[202:205], v153 offset:36864
	ds_read_b128 v[206:209], v153 offset:37888
	ds_read_b128 v[210:213], v153 offset:38912
	ds_read_b128 v[214:217], v153 offset:39936
	global_load_lds_dwordx4 v[224:225], off
	v_lshl_add_u64 v[224:225], s[38:39], 0, v[134:135]
	s_mov_b32 m0, s50
	s_nop 0
	global_load_lds_dwordx4 v[224:225], off
	s_waitcnt vmcnt(8)
	s_waitcnt lgkmcnt(0)
	s_setprio 1
	s_barrier
	v_mfma_f32_16x16x32_bf16 v[126:129], v[154:157], v[186:189], v[126:129]
	v_mfma_f32_16x16x32_bf16 v[122:125], v[162:165], v[186:189], v[122:125]
	v_mfma_f32_16x16x32_bf16 v[114:117], v[154:157], v[194:197], v[114:117]
	v_mfma_f32_16x16x32_bf16 v[106:109], v[162:165], v[194:197], v[106:109]
	v_mfma_f32_16x16x32_bf16 v[98:101], v[154:157], v[202:205], v[98:101]
	v_mfma_f32_16x16x32_bf16 v[90:93], v[162:165], v[202:205], v[90:93]
	v_mfma_f32_16x16x32_bf16 v[82:85], v[154:157], v[210:213], v[82:85]
	v_mfma_f32_16x16x32_bf16 v[74:77], v[162:165], v[210:213], v[74:77]
	v_mfma_f32_16x16x32_bf16 v[126:129], v[158:161], v[190:193], v[126:129]
	v_mfma_f32_16x16x32_bf16 v[122:125], v[166:169], v[190:193], v[122:125]
	v_mfma_f32_16x16x32_bf16 v[114:117], v[158:161], v[198:201], v[114:117]
	v_mfma_f32_16x16x32_bf16 v[106:109], v[166:169], v[198:201], v[106:109]
	v_mfma_f32_16x16x32_bf16 v[98:101], v[158:161], v[206:209], v[98:101]
	v_mfma_f32_16x16x32_bf16 v[90:93], v[166:169], v[206:209], v[90:93]
	v_mfma_f32_16x16x32_bf16 v[82:85], v[158:161], v[214:217], v[82:85]
	v_mfma_f32_16x16x32_bf16 v[74:77], v[166:169], v[214:217], v[74:77]
	v_mfma_f32_16x16x32_bf16 v[118:121], v[170:173], v[186:189], v[118:121]
	v_mfma_f32_16x16x32_bf16 v[110:113], v[178:181], v[186:189], v[110:113]
	v_mfma_f32_16x16x32_bf16 v[102:105], v[170:173], v[194:197], v[102:105]
	v_mfma_f32_16x16x32_bf16 v[94:97], v[178:181], v[194:197], v[94:97]
	v_mfma_f32_16x16x32_bf16 v[86:89], v[170:173], v[202:205], v[86:89]
	v_mfma_f32_16x16x32_bf16 v[78:81], v[178:181], v[202:205], v[78:81]
	v_mfma_f32_16x16x32_bf16 v[70:73], v[170:173], v[210:213], v[70:73]
	v_mfma_f32_16x16x32_bf16 v[66:69], v[178:181], v[210:213], v[66:69]
	v_mfma_f32_16x16x32_bf16 v[118:121], v[174:177], v[190:193], v[118:121]
	v_mfma_f32_16x16x32_bf16 v[110:113], v[182:185], v[190:193], v[110:113]
	v_mfma_f32_16x16x32_bf16 v[102:105], v[174:177], v[198:201], v[102:105]
	v_mfma_f32_16x16x32_bf16 v[94:97], v[182:185], v[198:201], v[94:97]
	v_mfma_f32_16x16x32_bf16 v[86:89], v[174:177], v[206:209], v[86:89]
	v_mfma_f32_16x16x32_bf16 v[78:81], v[182:185], v[206:209], v[78:81]
	v_mfma_f32_16x16x32_bf16 v[70:73], v[174:177], v[214:217], v[70:73]
	v_mfma_f32_16x16x32_bf16 v[66:69], v[182:185], v[214:217], v[66:69]
	s_barrier
	s_setprio 0
	s_add_i32 s38, s69, s47
	v_lshl_add_u64 v[148:149], v[148:149], 0, s[8:9]
	s_mov_b32 m0, s38
	ds_read_b128 v[186:189], v153 offset:49152
	ds_read_b128 v[190:193], v153 offset:50176
	ds_read_b128 v[194:197], v153 offset:51200
	ds_read_b128 v[198:201], v153 offset:52224
	ds_read_b128 v[202:205], v153 offset:53248
	ds_read_b128 v[206:209], v153 offset:54272
	ds_read_b128 v[210:213], v153 offset:55296
	ds_read_b128 v[214:217], v153 offset:56320
	global_load_lds_dwordx4 v[148:149], off
	s_add_i32 m0, s38, 0x2000
	s_add_u32 s36, s36, 0x100080
	v_lshl_add_u64 v[148:149], v[218:219], 0, s[8:9]
	s_addc_u32 s37, s37, 0
	s_add_i32 s38, s70, s47
	global_load_lds_dwordx4 v[148:149], off
	v_lshl_add_u64 v[148:149], s[36:37], 0, v[136:137]
	s_mov_b32 m0, s38
	s_nop 0
	global_load_lds_dwordx4 v[148:149], off
	v_lshl_add_u64 v[148:149], s[36:37], 0, v[132:133]
	s_add_i32 m0, s38, 0x2000
	s_nop 0
	global_load_lds_dwordx4 v[148:149], off
	v_lshl_add_u64 v[148:149], v[220:221], 0, s[8:9]
	s_mov_b32 m0, s52
	s_nop 0
	global_load_lds_dwordx4 v[148:149], off
	v_lshl_add_u64 v[148:149], v[222:223], 0, s[8:9]
	s_mov_b32 m0, s53
	s_nop 0
	global_load_lds_dwordx4 v[148:149], off
	s_waitcnt vmcnt(8)
	s_waitcnt lgkmcnt(0)
	s_setprio 1
	s_barrier
	v_mfma_f32_16x16x32_bf16 v[62:65], v[154:157], v[186:189], v[62:65]
	v_mfma_f32_16x16x32_bf16 v[58:61], v[162:165], v[186:189], v[58:61]
	v_mfma_f32_16x16x32_bf16 v[50:53], v[154:157], v[194:197], v[50:53]
	v_mfma_f32_16x16x32_bf16 v[42:45], v[162:165], v[194:197], v[42:45]
	v_mfma_f32_16x16x32_bf16 v[34:37], v[154:157], v[202:205], v[34:37]
	v_mfma_f32_16x16x32_bf16 v[26:29], v[162:165], v[202:205], v[26:29]
	v_mfma_f32_16x16x32_bf16 v[18:21], v[154:157], v[210:213], v[18:21]
	v_mfma_f32_16x16x32_bf16 v[10:13], v[162:165], v[210:213], v[10:13]
	v_mfma_f32_16x16x32_bf16 v[62:65], v[158:161], v[190:193], v[62:65]
	v_mfma_f32_16x16x32_bf16 v[58:61], v[166:169], v[190:193], v[58:61]
	v_mfma_f32_16x16x32_bf16 v[50:53], v[158:161], v[198:201], v[50:53]
	v_mfma_f32_16x16x32_bf16 v[42:45], v[166:169], v[198:201], v[42:45]
	v_mfma_f32_16x16x32_bf16 v[34:37], v[158:161], v[206:209], v[34:37]
	v_mfma_f32_16x16x32_bf16 v[26:29], v[166:169], v[206:209], v[26:29]
	v_mfma_f32_16x16x32_bf16 v[18:21], v[158:161], v[214:217], v[18:21]
	v_mfma_f32_16x16x32_bf16 v[10:13], v[166:169], v[214:217], v[10:13]
	v_mfma_f32_16x16x32_bf16 v[54:57], v[170:173], v[186:189], v[54:57]
	v_mfma_f32_16x16x32_bf16 v[46:49], v[178:181], v[186:189], v[46:49]
	v_mfma_f32_16x16x32_bf16 v[38:41], v[170:173], v[194:197], v[38:41]
	v_mfma_f32_16x16x32_bf16 v[30:33], v[178:181], v[194:197], v[30:33]
	v_mfma_f32_16x16x32_bf16 v[22:25], v[170:173], v[202:205], v[22:25]
	v_mfma_f32_16x16x32_bf16 v[14:17], v[178:181], v[202:205], v[14:17]
	v_mfma_f32_16x16x32_bf16 v[6:9], v[170:173], v[210:213], v[6:9]
	v_mfma_f32_16x16x32_bf16 v[2:5], v[178:181], v[210:213], v[2:5]
	v_mfma_f32_16x16x32_bf16 v[54:57], v[174:177], v[190:193], v[54:57]
	v_mfma_f32_16x16x32_bf16 v[46:49], v[182:185], v[190:193], v[46:49]
	v_mfma_f32_16x16x32_bf16 v[38:41], v[174:177], v[198:201], v[38:41]
	v_mfma_f32_16x16x32_bf16 v[30:33], v[182:185], v[198:201], v[30:33]
	v_mfma_f32_16x16x32_bf16 v[22:25], v[174:177], v[206:209], v[22:25]
	v_mfma_f32_16x16x32_bf16 v[14:17], v[182:185], v[206:209], v[14:17]
	v_mfma_f32_16x16x32_bf16 v[6:9], v[174:177], v[214:217], v[6:9]
	v_mfma_f32_16x16x32_bf16 v[2:5], v[182:185], v[214:217], v[2:5]
	s_barrier
	s_setprio 0
	s_add_i32 s68, s68, 2
	s_add_u32 s34, s34, 0x100
	s_addc_u32 s35, s35, 0
	s_add_u32 s63, s63, 0x100
	s_addc_u32 s65, s65, 0
	s_cmp_gt_u32 s68, 61
	s_cbranch_scc0 .LBB0_668
	s_and_b64 vcc, exec, s[12:13]
	s_cbranch_vccz .LBB0_671
	s_barrier

.LBB0_845:
	ds_read_b128 v[130:133], v238
	ds_read_b128 v[134:137], v238 offset:1024
	ds_read_b128 v[138:141], v238 offset:2048
	ds_read_b128 v[142:145], v238 offset:3072
	ds_read_b128 v[146:149], v239
	ds_read_b128 v[150:153], v239 offset:1024
	ds_read_b128 v[154:157], v239 offset:2048
	ds_read_b128 v[158:161], v239 offset:3072
	s_add_u32 s56, s2, 0x100
	s_addc_u32 s57, s3, 0
	s_cmp_eq_u32 s92, 28
	s_cselect_b32 s61, s49, s57
	s_cselect_b32 s60, s88, s56
	s_cselect_b32 s59, s47, s91
	s_cselect_b32 s58, s89, s90
	v_lshl_add_u64 v[194:195], s[2:3], 0, v[210:211]
	s_add_i32 m0, s55, 0xc000
	ds_read_b128 v[162:165], v240
	ds_read_b128 v[166:169], v240 offset:1024
	ds_read_b128 v[170:173], v240 offset:2048
	ds_read_b128 v[174:177], v240 offset:3072
	ds_read_b128 v[178:181], v240 offset:4096
	ds_read_b128 v[182:185], v240 offset:5120
	ds_read_b128 v[186:189], v240 offset:6144
	ds_read_b128 v[190:193], v240 offset:7168
	global_load_lds_dwordx4 v[194:195], off
	v_lshl_add_u64 v[194:195], s[2:3], 0, v[212:213]
	s_add_i32 m0, s55, 0xe000
	s_nop 0
	global_load_lds_dwordx4 v[194:195], off
	s_waitcnt vmcnt(8)
	s_waitcnt lgkmcnt(0)
	s_setprio 1
	s_barrier
	v_mfma_i32_16x16x64_i8 v[126:129], v[130:133], v[162:165], v[126:129]
	v_mfma_i32_16x16x64_i8 v[122:125], v[138:141], v[162:165], v[122:125]
	v_mfma_i32_16x16x64_i8 v[118:121], v[130:133], v[170:173], v[118:121]
	v_mfma_i32_16x16x64_i8 v[110:113], v[138:141], v[170:173], v[110:113]
	v_mfma_i32_16x16x64_i8 v[78:81], v[130:133], v[178:181], v[78:81]
	v_mfma_i32_16x16x64_i8 v[30:33], v[138:141], v[178:181], v[30:33]
	v_mfma_i32_16x16x64_i8 v[74:77], v[130:133], v[186:189], v[74:77]
	v_mfma_i32_16x16x64_i8 v[26:29], v[138:141], v[186:189], v[26:29]
	v_mfma_i32_16x16x64_i8 v[126:129], v[134:137], v[166:169], v[126:129]
	v_mfma_i32_16x16x64_i8 v[122:125], v[142:145], v[166:169], v[122:125]
	v_mfma_i32_16x16x64_i8 v[118:121], v[134:137], v[174:177], v[118:121]
	v_mfma_i32_16x16x64_i8 v[110:113], v[142:145], v[174:177], v[110:113]
	v_mfma_i32_16x16x64_i8 v[78:81], v[134:137], v[182:185], v[78:81]
	v_mfma_i32_16x16x64_i8 v[30:33], v[142:145], v[182:185], v[30:33]
	v_mfma_i32_16x16x64_i8 v[74:77], v[134:137], v[190:193], v[74:77]
	v_mfma_i32_16x16x64_i8 v[26:29], v[142:145], v[190:193], v[26:29]
	v_mfma_i32_16x16x64_i8 v[102:105], v[146:149], v[162:165], v[102:105]
	v_mfma_i32_16x16x64_i8 v[98:101], v[154:157], v[162:165], v[98:101]
	v_mfma_i32_16x16x64_i8 v[94:97], v[146:149], v[170:173], v[94:97]
	v_mfma_i32_16x16x64_i8 v[90:93], v[154:157], v[170:173], v[90:93]
	v_mfma_i32_16x16x64_i8 v[70:73], v[146:149], v[178:181], v[70:73]
	v_mfma_i32_16x16x64_i8 v[22:25], v[154:157], v[178:181], v[22:25]
	v_mfma_i32_16x16x64_i8 v[66:69], v[146:149], v[186:189], v[66:69]
	v_mfma_i32_16x16x64_i8 v[18:21], v[154:157], v[186:189], v[18:21]
	v_mfma_i32_16x16x64_i8 v[102:105], v[150:153], v[166:169], v[102:105]
	v_mfma_i32_16x16x64_i8 v[98:101], v[158:161], v[166:169], v[98:101]
	v_mfma_i32_16x16x64_i8 v[94:97], v[150:153], v[174:177], v[94:97]
	v_mfma_i32_16x16x64_i8 v[90:93], v[158:161], v[174:177], v[90:93]
	v_mfma_i32_16x16x64_i8 v[70:73], v[150:153], v[182:185], v[70:73]
	v_mfma_i32_16x16x64_i8 v[22:25], v[158:161], v[182:185], v[22:25]
	v_mfma_i32_16x16x64_i8 v[66:69], v[150:153], v[190:193], v[66:69]
	v_mfma_i32_16x16x64_i8 v[18:21], v[158:161], v[190:193], v[18:21]
	s_barrier
	s_setprio 0
	s_add_i32 s2, s84, s65
	v_lshl_add_u64 v[194:195], s[58:59], 0, v[206:207]
	s_mov_b32 m0, s2
	ds_read_b128 v[162:165], v240 offset:16384
	ds_read_b128 v[166:169], v240 offset:17408
	ds_read_b128 v[170:173], v240 offset:18432
	ds_read_b128 v[174:177], v240 offset:19456
	ds_read_b128 v[178:181], v240 offset:20480
	ds_read_b128 v[182:185], v240 offset:21504
	ds_read_b128 v[186:189], v240 offset:22528
	ds_read_b128 v[190:193], v240 offset:23552
	global_load_lds_dwordx4 v[194:195], off
	s_add_i32 m0, s2, 0x2000
	s_add_u32 s2, s58, 0x80000
	v_lshl_add_u64 v[196:197], s[58:59], 0, v[202:203]
	s_addc_u32 s3, s59, 0
	s_add_i32 s93, s85, s65
	global_load_lds_dwordx4 v[196:197], off
	v_lshl_add_u64 v[198:199], s[2:3], 0, v[206:207]
	s_mov_b32 m0, s93
	v_lshl_add_u64 v[200:201], s[60:61], 0, v[204:205]
	global_load_lds_dwordx4 v[198:199], off
	v_lshl_add_u64 v[198:199], s[2:3], 0, v[202:203]
	s_add_i32 m0, s93, 0x2000
	s_nop 0
	global_load_lds_dwordx4 v[198:199], off
	v_lshl_add_u64 v[198:199], s[60:61], 0, v[208:209]
	s_mov_b32 m0, s55
	s_nop 0
	global_load_lds_dwordx4 v[198:199], off
	s_mov_b32 m0, s69
	s_nop 0
	global_load_lds_dwordx4 v[200:201], off
	s_waitcnt vmcnt(8)
	s_waitcnt lgkmcnt(0)
	s_setprio 1
	s_barrier
	v_mfma_i32_16x16x64_i8 v[62:65], v[130:133], v[162:165], v[62:65]
	v_mfma_i32_16x16x64_i8 v[14:17], v[138:141], v[162:165], v[14:17]
	v_mfma_i32_16x16x64_i8 v[58:61], v[130:133], v[170:173], v[58:61]
	v_mfma_i32_16x16x64_i8 v[10:13], v[138:141], v[170:173], v[10:13]
	v_mfma_i32_16x16x64_i8 v[114:117], v[130:133], v[178:181], v[114:117]
	v_mfma_i32_16x16x64_i8 v[106:109], v[138:141], v[178:181], v[106:109]
	v_mfma_i32_16x16x64_i8 v[86:89], v[130:133], v[186:189], v[86:89]
	v_mfma_i32_16x16x64_i8 v[82:85], v[138:141], v[186:189], v[82:85]
	v_mfma_i32_16x16x64_i8 v[62:65], v[134:137], v[166:169], v[62:65]
	v_mfma_i32_16x16x64_i8 v[14:17], v[142:145], v[166:169], v[14:17]
	v_mfma_i32_16x16x64_i8 v[58:61], v[134:137], v[174:177], v[58:61]
	v_mfma_i32_16x16x64_i8 v[10:13], v[142:145], v[174:177], v[10:13]
	v_mfma_i32_16x16x64_i8 v[114:117], v[134:137], v[182:185], v[114:117]
	v_mfma_i32_16x16x64_i8 v[106:109], v[142:145], v[182:185], v[106:109]
	v_mfma_i32_16x16x64_i8 v[86:89], v[134:137], v[190:193], v[86:89]
	v_mfma_i32_16x16x64_i8 v[82:85], v[142:145], v[190:193], v[82:85]
	v_mfma_i32_16x16x64_i8 v[50:53], v[146:149], v[162:165], v[50:53]
	v_mfma_i32_16x16x64_i8 v[6:9], v[154:157], v[162:165], v[6:9]
	v_mfma_i32_16x16x64_i8 v[42:45], v[146:149], v[170:173], v[42:45]
	v_mfma_i32_16x16x64_i8 v[2:5], v[154:157], v[170:173], v[2:5]
	v_mfma_i32_16x16x64_i8 v[54:57], v[146:149], v[178:181], v[54:57]
	v_mfma_i32_16x16x64_i8 v[46:49], v[154:157], v[178:181], v[46:49]
	v_mfma_i32_16x16x64_i8 v[38:41], v[146:149], v[186:189], v[38:41]
	v_mfma_i32_16x16x64_i8 v[34:37], v[154:157], v[186:189], v[34:37]
	v_mfma_i32_16x16x64_i8 v[50:53], v[150:153], v[166:169], v[50:53]
	v_mfma_i32_16x16x64_i8 v[6:9], v[158:161], v[166:169], v[6:9]
	v_mfma_i32_16x16x64_i8 v[42:45], v[150:153], v[174:177], v[42:45]
	v_mfma_i32_16x16x64_i8 v[2:5], v[158:161], v[174:177], v[2:5]
	v_mfma_i32_16x16x64_i8 v[54:57], v[150:153], v[182:185], v[54:57]
	v_mfma_i32_16x16x64_i8 v[46:49], v[158:161], v[182:185], v[46:49]
	v_mfma_i32_16x16x64_i8 v[38:41], v[150:153], v[190:193], v[38:41]
	v_mfma_i32_16x16x64_i8 v[34:37], v[158:161], v[190:193], v[34:37]
	s_barrier
	s_setprio 0
	s_add_i32 s93, 0, 0x18000
	s_add_i32 s94, 0, 0x1c000
	v_add_u32_e32 v142, s93, v237
	v_add_u32_e32 v158, s94, v237
	ds_read_b128 v[130:133], v142
	ds_read_b128 v[134:137], v142 offset:1024
	ds_read_b128 v[138:141], v142 offset:2048
	ds_read_b128 v[142:145], v142 offset:3072
	ds_read_b128 v[146:149], v158
	ds_read_b128 v[150:153], v158 offset:1024
	ds_read_b128 v[154:157], v158 offset:2048
	ds_read_b128 v[158:161], v158 offset:3072
	s_add_u32 s2, s60, 0x4000
	s_addc_u32 s3, s61, 0
	s_mov_b32 m0, s70
	v_lshl_add_u64 v[220:221], s[2:3], 0, v[208:209]
	ds_read_b128 v[162:165], v240 offset:32768
	ds_read_b128 v[166:169], v240 offset:33792
	ds_read_b128 v[170:173], v240 offset:34816
	ds_read_b128 v[174:177], v240 offset:35840
	ds_read_b128 v[178:181], v240 offset:36864
	ds_read_b128 v[182:185], v240 offset:37888
	ds_read_b128 v[186:189], v240 offset:38912
	ds_read_b128 v[190:193], v240 offset:39936
	global_load_lds_dwordx4 v[220:221], off
	v_lshl_add_u64 v[220:221], s[2:3], 0, v[204:205]
	s_mov_b32 m0, s71
	s_nop 0
	global_load_lds_dwordx4 v[220:221], off
	s_waitcnt vmcnt(8)
	s_waitcnt lgkmcnt(0)
	s_setprio 1
	s_barrier
	v_mfma_i32_16x16x64_i8 v[126:129], v[130:133], v[162:165], v[126:129]
	v_mfma_i32_16x16x64_i8 v[122:125], v[138:141], v[162:165], v[122:125]
	v_mfma_i32_16x16x64_i8 v[118:121], v[130:133], v[170:173], v[118:121]
	v_mfma_i32_16x16x64_i8 v[110:113], v[138:141], v[170:173], v[110:113]
	v_mfma_i32_16x16x64_i8 v[78:81], v[130:133], v[178:181], v[78:81]
	v_mfma_i32_16x16x64_i8 v[30:33], v[138:141], v[178:181], v[30:33]
	v_mfma_i32_16x16x64_i8 v[74:77], v[130:133], v[186:189], v[74:77]
	v_mfma_i32_16x16x64_i8 v[26:29], v[138:141], v[186:189], v[26:29]
	v_mfma_i32_16x16x64_i8 v[126:129], v[134:137], v[166:169], v[126:129]
	v_mfma_i32_16x16x64_i8 v[122:125], v[142:145], v[166:169], v[122:125]
	v_mfma_i32_16x16x64_i8 v[118:121], v[134:137], v[174:177], v[118:121]
	v_mfma_i32_16x16x64_i8 v[110:113], v[142:145], v[174:177], v[110:113]
	v_mfma_i32_16x16x64_i8 v[78:81], v[134:137], v[182:185], v[78:81]
	v_mfma_i32_16x16x64_i8 v[30:33], v[142:145], v[182:185], v[30:33]
	v_mfma_i32_16x16x64_i8 v[74:77], v[134:137], v[190:193], v[74:77]
	v_mfma_i32_16x16x64_i8 v[26:29], v[142:145], v[190:193], v[26:29]
	v_mfma_i32_16x16x64_i8 v[102:105], v[146:149], v[162:165], v[102:105]
	v_mfma_i32_16x16x64_i8 v[98:101], v[154:157], v[162:165], v[98:101]
	v_mfma_i32_16x16x64_i8 v[94:97], v[146:149], v[170:173], v[94:97]
	v_mfma_i32_16x16x64_i8 v[90:93], v[154:157], v[170:173], v[90:93]
	v_mfma_i32_16x16x64_i8 v[70:73], v[146:149], v[178:181], v[70:73]
	v_mfma_i32_16x16x64_i8 v[22:25], v[154:157], v[178:181], v[22:25]
	v_mfma_i32_16x16x64_i8 v[66:69], v[146:149], v[186:189], v[66:69]
	v_mfma_i32_16x16x64_i8 v[18:21], v[154:157], v[186:189], v[18:21]
	v_mfma_i32_16x16x64_i8 v[102:105], v[150:153], v[166:169], v[102:105]
	v_mfma_i32_16x16x64_i8 v[98:101], v[158:161], v[166:169], v[98:101]
	v_mfma_i32_16x16x64_i8 v[94:97], v[150:153], v[174:177], v[94:97]
	v_mfma_i32_16x16x64_i8 v[90:93], v[158:161], v[174:177], v[90:93]
	v_mfma_i32_16x16x64_i8 v[70:73], v[150:153], v[182:185], v[70:73]
	v_mfma_i32_16x16x64_i8 v[22:25], v[158:161], v[182:185], v[22:25]
	v_mfma_i32_16x16x64_i8 v[66:69], v[150:153], v[190:193], v[66:69]
	v_mfma_i32_16x16x64_i8 v[18:21], v[158:161], v[190:193], v[18:21]
	s_barrier
	s_setprio 0
	s_add_i32 s2, s93, s65
	v_lshl_add_u64 v[194:195], v[194:195], 0, s[36:37]
	s_mov_b32 m0, s2
	ds_read_b128 v[162:165], v240 offset:49152
	ds_read_b128 v[166:169], v240 offset:50176
	ds_read_b128 v[170:173], v240 offset:51200
	ds_read_b128 v[174:177], v240 offset:52224
	ds_read_b128 v[178:181], v240 offset:53248
	ds_read_b128 v[182:185], v240 offset:54272
	ds_read_b128 v[186:189], v240 offset:55296
	ds_read_b128 v[190:193], v240 offset:56320
	global_load_lds_dwordx4 v[194:195], off
	s_add_i32 m0, s2, 0x2000
	s_add_u32 s2, s58, 0x80080
	v_lshl_add_u64 v[194:195], v[196:197], 0, s[36:37]
	s_addc_u32 s3, s59, 0
	s_add_i32 s58, s94, s65
	global_load_lds_dwordx4 v[194:195], off
	v_lshl_add_u64 v[194:195], s[2:3], 0, v[206:207]
	s_mov_b32 m0, s58
	s_nop 0
	global_load_lds_dwordx4 v[194:195], off
	v_lshl_add_u64 v[194:195], s[2:3], 0, v[202:203]
	s_add_i32 m0, s58, 0x2000
	s_nop 0
	global_load_lds_dwordx4 v[194:195], off
	v_lshl_add_u64 v[194:195], v[198:199], 0, s[36:37]
	s_mov_b32 m0, s78
	s_nop 0
	global_load_lds_dwordx4 v[194:195], off
	v_lshl_add_u64 v[194:195], v[200:201], 0, s[36:37]
	s_mov_b32 m0, s79
	s_nop 0
	global_load_lds_dwordx4 v[194:195], off
	s_waitcnt vmcnt(8)
	s_waitcnt lgkmcnt(0)
	s_setprio 1
	s_barrier
	v_mfma_i32_16x16x64_i8 v[62:65], v[130:133], v[162:165], v[62:65]
	v_mfma_i32_16x16x64_i8 v[14:17], v[138:141], v[162:165], v[14:17]
	v_mfma_i32_16x16x64_i8 v[58:61], v[130:133], v[170:173], v[58:61]
	v_mfma_i32_16x16x64_i8 v[10:13], v[138:141], v[170:173], v[10:13]
	v_mfma_i32_16x16x64_i8 v[114:117], v[130:133], v[178:181], v[114:117]
	v_mfma_i32_16x16x64_i8 v[106:109], v[138:141], v[178:181], v[106:109]
	v_mfma_i32_16x16x64_i8 v[86:89], v[130:133], v[186:189], v[86:89]
	v_mfma_i32_16x16x64_i8 v[82:85], v[138:141], v[186:189], v[82:85]
	v_mfma_i32_16x16x64_i8 v[62:65], v[134:137], v[166:169], v[62:65]
	v_mfma_i32_16x16x64_i8 v[14:17], v[142:145], v[166:169], v[14:17]
	v_mfma_i32_16x16x64_i8 v[58:61], v[134:137], v[174:177], v[58:61]
	v_mfma_i32_16x16x64_i8 v[10:13], v[142:145], v[174:177], v[10:13]
	v_mfma_i32_16x16x64_i8 v[114:117], v[134:137], v[182:185], v[114:117]
	v_mfma_i32_16x16x64_i8 v[106:109], v[142:145], v[182:185], v[106:109]
	v_mfma_i32_16x16x64_i8 v[86:89], v[134:137], v[190:193], v[86:89]
	v_mfma_i32_16x16x64_i8 v[82:85], v[142:145], v[190:193], v[82:85]
	v_mfma_i32_16x16x64_i8 v[50:53], v[146:149], v[162:165], v[50:53]
	v_mfma_i32_16x16x64_i8 v[6:9], v[154:157], v[162:165], v[6:9]
	v_mfma_i32_16x16x64_i8 v[42:45], v[146:149], v[170:173], v[42:45]
	v_mfma_i32_16x16x64_i8 v[2:5], v[154:157], v[170:173], v[2:5]
	v_mfma_i32_16x16x64_i8 v[54:57], v[146:149], v[178:181], v[54:57]
	v_mfma_i32_16x16x64_i8 v[46:49], v[154:157], v[178:181], v[46:49]
	v_mfma_i32_16x16x64_i8 v[38:41], v[146:149], v[186:189], v[38:41]
	v_mfma_i32_16x16x64_i8 v[34:37], v[154:157], v[186:189], v[34:37]
	v_mfma_i32_16x16x64_i8 v[50:53], v[150:153], v[166:169], v[50:53]
	v_mfma_i32_16x16x64_i8 v[6:9], v[158:161], v[166:169], v[6:9]
	v_mfma_i32_16x16x64_i8 v[42:45], v[150:153], v[174:177], v[42:45]
	v_mfma_i32_16x16x64_i8 v[2:5], v[158:161], v[174:177], v[2:5]
	v_mfma_i32_16x16x64_i8 v[54:57], v[150:153], v[182:185], v[54:57]
	v_mfma_i32_16x16x64_i8 v[46:49], v[158:161], v[182:185], v[46:49]
	v_mfma_i32_16x16x64_i8 v[38:41], v[150:153], v[190:193], v[38:41]
	v_mfma_i32_16x16x64_i8 v[34:37], v[158:161], v[190:193], v[34:37]
	s_barrier
	s_setprio 0
	s_add_i32 s92, s92, 2
	s_add_u32 s90, s90, 0x100
	s_addc_u32 s91, s91, 0
	s_cmp_gt_u32 s92, 29
	s_mov_b64 s[2:3], s[56:57]
	s_cbranch_scc0 .LBB0_845
	s_and_b64 vcc, exec, s[38:39]
	s_cbranch_vccz .LBB0_848
	s_barrier

.LBB0_1099:
	ds_read_b128 v[130:133], v167
	ds_read_b128 v[134:137], v167 offset:1024
	ds_read_b128 v[138:141], v167 offset:2048
	ds_read_b128 v[142:145], v167 offset:3072
	ds_read_b128 v[170:173], v168
	ds_read_b128 v[174:177], v168 offset:1024
	ds_read_b128 v[178:181], v168 offset:2048
	ds_read_b128 v[182:185], v168 offset:3072
	s_add_u32 s30, s28, 0x100
	s_addc_u32 s31, s29, 0
	s_cmpk_eq_i32 s72, 0x52
	s_cselect_b32 s37, s3, s31
	s_cselect_b32 s36, s2, s30
	s_cselect_b32 s35, s27, s71
	s_cselect_b32 s34, s26, s70
	v_lshl_add_u64 v[162:163], s[28:29], 0, v[154:155]
	s_add_i32 m0, s47, 0xc000
	ds_read_b128 v[186:189], v169
	ds_read_b128 v[190:193], v169 offset:1024
	ds_read_b128 v[194:197], v169 offset:2048
	ds_read_b128 v[198:201], v169 offset:3072
	ds_read_b128 v[202:205], v169 offset:4096
	ds_read_b128 v[206:209], v169 offset:5120
	ds_read_b128 v[210:213], v169 offset:6144
	ds_read_b128 v[214:217], v169 offset:7168
	global_load_lds_dwordx4 v[162:163], off
	v_lshl_add_u64 v[162:163], s[28:29], 0, v[156:157]
	s_add_i32 m0, s47, 0xe000
	s_nop 0
	global_load_lds_dwordx4 v[162:163], off
	s_waitcnt vmcnt(8)
	s_waitcnt lgkmcnt(0)
	s_setprio 1
	s_barrier
	v_mfma_i32_16x16x64_i8 v[126:129], v[130:133], v[186:189], v[126:129]
	v_mfma_i32_16x16x64_i8 v[122:125], v[138:141], v[186:189], v[122:125]
	v_mfma_i32_16x16x64_i8 v[110:113], v[130:133], v[194:197], v[110:113]
	v_mfma_i32_16x16x64_i8 v[106:109], v[138:141], v[194:197], v[106:109]
	v_mfma_i32_16x16x64_i8 v[94:97], v[130:133], v[202:205], v[94:97]
	v_mfma_i32_16x16x64_i8 v[90:93], v[138:141], v[202:205], v[90:93]
	v_mfma_i32_16x16x64_i8 v[78:81], v[130:133], v[210:213], v[78:81]
	v_mfma_i32_16x16x64_i8 v[74:77], v[138:141], v[210:213], v[74:77]
	v_mfma_i32_16x16x64_i8 v[126:129], v[134:137], v[190:193], v[126:129]
	v_mfma_i32_16x16x64_i8 v[122:125], v[142:145], v[190:193], v[122:125]
	v_mfma_i32_16x16x64_i8 v[110:113], v[134:137], v[198:201], v[110:113]
	v_mfma_i32_16x16x64_i8 v[106:109], v[142:145], v[198:201], v[106:109]
	v_mfma_i32_16x16x64_i8 v[94:97], v[134:137], v[206:209], v[94:97]
	v_mfma_i32_16x16x64_i8 v[90:93], v[142:145], v[206:209], v[90:93]
	v_mfma_i32_16x16x64_i8 v[78:81], v[134:137], v[214:217], v[78:81]
	v_mfma_i32_16x16x64_i8 v[74:77], v[142:145], v[214:217], v[74:77]
	v_mfma_i32_16x16x64_i8 v[118:121], v[170:173], v[186:189], v[118:121]
	v_mfma_i32_16x16x64_i8 v[114:117], v[178:181], v[186:189], v[114:117]
	v_mfma_i32_16x16x64_i8 v[102:105], v[170:173], v[194:197], v[102:105]
	v_mfma_i32_16x16x64_i8 v[98:101], v[178:181], v[194:197], v[98:101]
	v_mfma_i32_16x16x64_i8 v[86:89], v[170:173], v[202:205], v[86:89]
	v_mfma_i32_16x16x64_i8 v[82:85], v[178:181], v[202:205], v[82:85]
	v_mfma_i32_16x16x64_i8 v[70:73], v[170:173], v[210:213], v[70:73]
	v_mfma_i32_16x16x64_i8 v[66:69], v[178:181], v[210:213], v[66:69]
	v_mfma_i32_16x16x64_i8 v[118:121], v[174:177], v[190:193], v[118:121]
	v_mfma_i32_16x16x64_i8 v[114:117], v[182:185], v[190:193], v[114:117]
	v_mfma_i32_16x16x64_i8 v[102:105], v[174:177], v[198:201], v[102:105]
	v_mfma_i32_16x16x64_i8 v[98:101], v[182:185], v[198:201], v[98:101]
	v_mfma_i32_16x16x64_i8 v[86:89], v[174:177], v[206:209], v[86:89]
	v_mfma_i32_16x16x64_i8 v[82:85], v[182:185], v[206:209], v[82:85]
	v_mfma_i32_16x16x64_i8 v[70:73], v[174:177], v[214:217], v[70:73]
	v_mfma_i32_16x16x64_i8 v[66:69], v[182:185], v[214:217], v[66:69]
	s_barrier
	s_setprio 0
	s_add_i32 s28, s56, s46
	v_lshl_add_u64 v[162:163], s[34:35], 0, v[150:151]
	s_mov_b32 m0, s28
	ds_read_b128 v[186:189], v169 offset:16384
	ds_read_b128 v[190:193], v169 offset:17408
	ds_read_b128 v[194:197], v169 offset:18432
	ds_read_b128 v[198:201], v169 offset:19456
	ds_read_b128 v[202:205], v169 offset:20480
	ds_read_b128 v[206:209], v169 offset:21504
	ds_read_b128 v[210:213], v169 offset:22528
	ds_read_b128 v[214:217], v169 offset:23552
	global_load_lds_dwordx4 v[162:163], off
	s_add_i32 m0, s28, 0x2000
	s_add_u32 s28, s34, 0x158000
	v_lshl_add_u64 v[218:219], s[34:35], 0, v[146:147]
	s_addc_u32 s29, s35, 0
	s_add_i32 s73, s57, s46
	global_load_lds_dwordx4 v[218:219], off
	v_lshl_add_u64 v[220:221], s[28:29], 0, v[150:151]
	s_mov_b32 m0, s73
	v_lshl_add_u64 v[222:223], s[36:37], 0, v[148:149]
	global_load_lds_dwordx4 v[220:221], off
	v_lshl_add_u64 v[220:221], s[28:29], 0, v[146:147]
	s_add_i32 m0, s73, 0x2000
	s_nop 0
	global_load_lds_dwordx4 v[220:221], off
	v_lshl_add_u64 v[220:221], s[36:37], 0, v[152:153]
	s_mov_b32 m0, s47
	s_nop 0
	global_load_lds_dwordx4 v[220:221], off
	s_mov_b32 m0, s48
	s_nop 0
	global_load_lds_dwordx4 v[222:223], off
	s_waitcnt vmcnt(8)
	s_waitcnt lgkmcnt(0)
	s_setprio 1
	s_barrier
	v_mfma_i32_16x16x64_i8 v[62:65], v[130:133], v[186:189], v[62:65]
	v_mfma_i32_16x16x64_i8 v[58:61], v[138:141], v[186:189], v[58:61]
	v_mfma_i32_16x16x64_i8 v[46:49], v[130:133], v[194:197], v[46:49]
	v_mfma_i32_16x16x64_i8 v[42:45], v[138:141], v[194:197], v[42:45]
	v_mfma_i32_16x16x64_i8 v[30:33], v[130:133], v[202:205], v[30:33]
	v_mfma_i32_16x16x64_i8 v[26:29], v[138:141], v[202:205], v[26:29]
	v_mfma_i32_16x16x64_i8 v[14:17], v[130:133], v[210:213], v[14:17]
	v_mfma_i32_16x16x64_i8 v[10:13], v[138:141], v[210:213], v[10:13]
	v_mfma_i32_16x16x64_i8 v[62:65], v[134:137], v[190:193], v[62:65]
	v_mfma_i32_16x16x64_i8 v[58:61], v[142:145], v[190:193], v[58:61]
	v_mfma_i32_16x16x64_i8 v[46:49], v[134:137], v[198:201], v[46:49]
	v_mfma_i32_16x16x64_i8 v[42:45], v[142:145], v[198:201], v[42:45]
	v_mfma_i32_16x16x64_i8 v[30:33], v[134:137], v[206:209], v[30:33]
	v_mfma_i32_16x16x64_i8 v[26:29], v[142:145], v[206:209], v[26:29]
	v_mfma_i32_16x16x64_i8 v[14:17], v[134:137], v[214:217], v[14:17]
	v_mfma_i32_16x16x64_i8 v[10:13], v[142:145], v[214:217], v[10:13]
	v_mfma_i32_16x16x64_i8 v[54:57], v[170:173], v[186:189], v[54:57]
	v_mfma_i32_16x16x64_i8 v[50:53], v[178:181], v[186:189], v[50:53]
	v_mfma_i32_16x16x64_i8 v[38:41], v[170:173], v[194:197], v[38:41]
	v_mfma_i32_16x16x64_i8 v[34:37], v[178:181], v[194:197], v[34:37]
	v_mfma_i32_16x16x64_i8 v[22:25], v[170:173], v[202:205], v[22:25]
	v_mfma_i32_16x16x64_i8 v[18:21], v[178:181], v[202:205], v[18:21]
	v_mfma_i32_16x16x64_i8 v[6:9], v[170:173], v[210:213], v[6:9]
	v_mfma_i32_16x16x64_i8 v[2:5], v[178:181], v[210:213], v[2:5]
	v_mfma_i32_16x16x64_i8 v[54:57], v[174:177], v[190:193], v[54:57]
	v_mfma_i32_16x16x64_i8 v[50:53], v[182:185], v[190:193], v[50:53]
	v_mfma_i32_16x16x64_i8 v[38:41], v[174:177], v[198:201], v[38:41]
	v_mfma_i32_16x16x64_i8 v[34:37], v[182:185], v[198:201], v[34:37]
	v_mfma_i32_16x16x64_i8 v[22:25], v[174:177], v[206:209], v[22:25]
	v_mfma_i32_16x16x64_i8 v[18:21], v[182:185], v[206:209], v[18:21]
	v_mfma_i32_16x16x64_i8 v[6:9], v[174:177], v[214:217], v[6:9]
	v_mfma_i32_16x16x64_i8 v[2:5], v[182:185], v[214:217], v[2:5]
	s_barrier
	s_setprio 0
	s_add_i32 s73, 0, 0x18000
	s_add_i32 s74, 0, 0x1c000
	v_add_u32_e32 v142, s73, v166
	v_add_u32_e32 v182, s74, v166
	ds_read_b128 v[130:133], v142
	ds_read_b128 v[134:137], v142 offset:1024
	ds_read_b128 v[138:141], v142 offset:2048
	ds_read_b128 v[142:145], v142 offset:3072
	ds_read_b128 v[170:173], v182
	ds_read_b128 v[174:177], v182 offset:1024
	ds_read_b128 v[178:181], v182 offset:2048
	ds_read_b128 v[182:185], v182 offset:3072
	s_add_u32 s28, s36, 0x158000
	s_addc_u32 s29, s37, 0
	s_mov_b32 m0, s49
	v_lshl_add_u64 v[224:225], s[28:29], 0, v[152:153]
	ds_read_b128 v[186:189], v169 offset:32768
	ds_read_b128 v[190:193], v169 offset:33792
	ds_read_b128 v[194:197], v169 offset:34816
	ds_read_b128 v[198:201], v169 offset:35840
	ds_read_b128 v[202:205], v169 offset:36864
	ds_read_b128 v[206:209], v169 offset:37888
	ds_read_b128 v[210:213], v169 offset:38912
	ds_read_b128 v[214:217], v169 offset:39936
	global_load_lds_dwordx4 v[224:225], off
	v_lshl_add_u64 v[224:225], s[28:29], 0, v[148:149]
	s_mov_b32 m0, s50
	s_nop 0
	global_load_lds_dwordx4 v[224:225], off
	s_waitcnt vmcnt(8)
	s_waitcnt lgkmcnt(0)
	s_setprio 1
	s_barrier
	v_mfma_i32_16x16x64_i8 v[126:129], v[130:133], v[186:189], v[126:129]
	v_mfma_i32_16x16x64_i8 v[122:125], v[138:141], v[186:189], v[122:125]
	v_mfma_i32_16x16x64_i8 v[110:113], v[130:133], v[194:197], v[110:113]
	v_mfma_i32_16x16x64_i8 v[106:109], v[138:141], v[194:197], v[106:109]
	v_mfma_i32_16x16x64_i8 v[94:97], v[130:133], v[202:205], v[94:97]
	v_mfma_i32_16x16x64_i8 v[90:93], v[138:141], v[202:205], v[90:93]
	v_mfma_i32_16x16x64_i8 v[78:81], v[130:133], v[210:213], v[78:81]
	v_mfma_i32_16x16x64_i8 v[74:77], v[138:141], v[210:213], v[74:77]
	v_mfma_i32_16x16x64_i8 v[126:129], v[134:137], v[190:193], v[126:129]
	v_mfma_i32_16x16x64_i8 v[122:125], v[142:145], v[190:193], v[122:125]
	v_mfma_i32_16x16x64_i8 v[110:113], v[134:137], v[198:201], v[110:113]
	v_mfma_i32_16x16x64_i8 v[106:109], v[142:145], v[198:201], v[106:109]
	v_mfma_i32_16x16x64_i8 v[94:97], v[134:137], v[206:209], v[94:97]
	v_mfma_i32_16x16x64_i8 v[90:93], v[142:145], v[206:209], v[90:93]
	v_mfma_i32_16x16x64_i8 v[78:81], v[134:137], v[214:217], v[78:81]
	v_mfma_i32_16x16x64_i8 v[74:77], v[142:145], v[214:217], v[74:77]
	v_mfma_i32_16x16x64_i8 v[118:121], v[170:173], v[186:189], v[118:121]
	v_mfma_i32_16x16x64_i8 v[114:117], v[178:181], v[186:189], v[114:117]
	v_mfma_i32_16x16x64_i8 v[102:105], v[170:173], v[194:197], v[102:105]
	v_mfma_i32_16x16x64_i8 v[98:101], v[178:181], v[194:197], v[98:101]
	v_mfma_i32_16x16x64_i8 v[86:89], v[170:173], v[202:205], v[86:89]
	v_mfma_i32_16x16x64_i8 v[82:85], v[178:181], v[202:205], v[82:85]
	v_mfma_i32_16x16x64_i8 v[70:73], v[170:173], v[210:213], v[70:73]
	v_mfma_i32_16x16x64_i8 v[66:69], v[178:181], v[210:213], v[66:69]
	v_mfma_i32_16x16x64_i8 v[118:121], v[174:177], v[190:193], v[118:121]
	v_mfma_i32_16x16x64_i8 v[114:117], v[182:185], v[190:193], v[114:117]
	v_mfma_i32_16x16x64_i8 v[102:105], v[174:177], v[198:201], v[102:105]
	v_mfma_i32_16x16x64_i8 v[98:101], v[182:185], v[198:201], v[98:101]
	v_mfma_i32_16x16x64_i8 v[86:89], v[174:177], v[206:209], v[86:89]
	v_mfma_i32_16x16x64_i8 v[82:85], v[182:185], v[206:209], v[82:85]
	v_mfma_i32_16x16x64_i8 v[70:73], v[174:177], v[214:217], v[70:73]
	v_mfma_i32_16x16x64_i8 v[66:69], v[182:185], v[214:217], v[66:69]
	s_barrier
	s_setprio 0
	s_add_i32 s28, s73, s46
	v_lshl_add_u64 v[162:163], v[162:163], 0, s[14:15]
	s_mov_b32 m0, s28
	ds_read_b128 v[186:189], v169 offset:49152
	ds_read_b128 v[190:193], v169 offset:50176
	ds_read_b128 v[194:197], v169 offset:51200
	ds_read_b128 v[198:201], v169 offset:52224
	ds_read_b128 v[202:205], v169 offset:53248
	ds_read_b128 v[206:209], v169 offset:54272
	ds_read_b128 v[210:213], v169 offset:55296
	ds_read_b128 v[214:217], v169 offset:56320
	global_load_lds_dwordx4 v[162:163], off
	s_add_i32 m0, s28, 0x2000
	s_add_u32 s28, s34, 0x158080
	v_lshl_add_u64 v[162:163], v[218:219], 0, s[14:15]
	s_addc_u32 s29, s35, 0
	s_add_i32 s34, s74, s46
	global_load_lds_dwordx4 v[162:163], off
	v_lshl_add_u64 v[162:163], s[28:29], 0, v[150:151]
	s_mov_b32 m0, s34
	s_nop 0
	global_load_lds_dwordx4 v[162:163], off
	v_lshl_add_u64 v[162:163], s[28:29], 0, v[146:147]
	s_add_i32 m0, s34, 0x2000
	s_nop 0
	global_load_lds_dwordx4 v[162:163], off
	v_lshl_add_u64 v[162:163], v[220:221], 0, s[14:15]
	s_mov_b32 m0, s54
	s_nop 0
	global_load_lds_dwordx4 v[162:163], off
	v_lshl_add_u64 v[162:163], v[222:223], 0, s[14:15]
	s_mov_b32 m0, s55
	s_nop 0
	global_load_lds_dwordx4 v[162:163], off
	s_waitcnt vmcnt(8)
	s_waitcnt lgkmcnt(0)
	s_setprio 1
	s_barrier
	v_mfma_i32_16x16x64_i8 v[62:65], v[130:133], v[186:189], v[62:65]
	v_mfma_i32_16x16x64_i8 v[58:61], v[138:141], v[186:189], v[58:61]
	v_mfma_i32_16x16x64_i8 v[46:49], v[130:133], v[194:197], v[46:49]
	v_mfma_i32_16x16x64_i8 v[42:45], v[138:141], v[194:197], v[42:45]
	v_mfma_i32_16x16x64_i8 v[30:33], v[130:133], v[202:205], v[30:33]
	v_mfma_i32_16x16x64_i8 v[26:29], v[138:141], v[202:205], v[26:29]
	v_mfma_i32_16x16x64_i8 v[14:17], v[130:133], v[210:213], v[14:17]
	v_mfma_i32_16x16x64_i8 v[10:13], v[138:141], v[210:213], v[10:13]
	v_mfma_i32_16x16x64_i8 v[62:65], v[134:137], v[190:193], v[62:65]
	v_mfma_i32_16x16x64_i8 v[58:61], v[142:145], v[190:193], v[58:61]
	v_mfma_i32_16x16x64_i8 v[46:49], v[134:137], v[198:201], v[46:49]
	v_mfma_i32_16x16x64_i8 v[42:45], v[142:145], v[198:201], v[42:45]
	v_mfma_i32_16x16x64_i8 v[30:33], v[134:137], v[206:209], v[30:33]
	v_mfma_i32_16x16x64_i8 v[26:29], v[142:145], v[206:209], v[26:29]
	v_mfma_i32_16x16x64_i8 v[14:17], v[134:137], v[214:217], v[14:17]
	v_mfma_i32_16x16x64_i8 v[10:13], v[142:145], v[214:217], v[10:13]
	v_mfma_i32_16x16x64_i8 v[54:57], v[170:173], v[186:189], v[54:57]
	v_mfma_i32_16x16x64_i8 v[50:53], v[178:181], v[186:189], v[50:53]
	v_mfma_i32_16x16x64_i8 v[38:41], v[170:173], v[194:197], v[38:41]
	v_mfma_i32_16x16x64_i8 v[34:37], v[178:181], v[194:197], v[34:37]
	v_mfma_i32_16x16x64_i8 v[22:25], v[170:173], v[202:205], v[22:25]
	v_mfma_i32_16x16x64_i8 v[18:21], v[178:181], v[202:205], v[18:21]
	v_mfma_i32_16x16x64_i8 v[6:9], v[170:173], v[210:213], v[6:9]
	v_mfma_i32_16x16x64_i8 v[2:5], v[178:181], v[210:213], v[2:5]
	v_mfma_i32_16x16x64_i8 v[54:57], v[174:177], v[190:193], v[54:57]
	v_mfma_i32_16x16x64_i8 v[50:53], v[182:185], v[190:193], v[50:53]
	v_mfma_i32_16x16x64_i8 v[38:41], v[174:177], v[198:201], v[38:41]
	v_mfma_i32_16x16x64_i8 v[34:37], v[182:185], v[198:201], v[34:37]
	v_mfma_i32_16x16x64_i8 v[22:25], v[174:177], v[206:209], v[22:25]
	v_mfma_i32_16x16x64_i8 v[18:21], v[182:185], v[206:209], v[18:21]
	v_mfma_i32_16x16x64_i8 v[6:9], v[174:177], v[214:217], v[6:9]
	v_mfma_i32_16x16x64_i8 v[2:5], v[182:185], v[214:217], v[2:5]
	s_barrier
	s_setprio 0
	s_add_i32 s72, s72, 2
	s_add_u32 s70, s70, 0x100
	s_addc_u32 s71, s71, 0
	s_cmpk_gt_u32 s72, 0x53
	s_mov_b64 s[28:29], s[30:31]
	s_cbranch_scc0 .LBB0_1099
	s_and_b64 vcc, exec, s[16:17]
	s_cbranch_vccz .LBB0_1102
	s_barrier

.LBB0_1246:
	ds_read_b128 v[130:133], v193
	ds_read_b128 v[134:137], v193 offset:1024
	ds_read_b128 v[138:141], v193 offset:2048
	ds_read_b128 v[142:145], v193 offset:3072
	ds_read_b128 v[162:165], v194
	ds_read_b128 v[166:169], v194 offset:1024
	ds_read_b128 v[170:173], v194 offset:2048
	ds_read_b128 v[174:177], v194 offset:3072
	s_add_u32 s30, s28, 0xfff00080
	s_addc_u32 s31, s29, -1
	s_cmp_eq_u32 s68, 60
	s_cselect_b32 s35, s3, s31
	s_cselect_b32 s34, s23, s30
	s_cselect_b32 s31, s17, s65
	s_cselect_b32 s30, s62, s63
	v_lshl_add_u64 v[216:217], s[28:29], 0, v[154:155]
	s_add_i32 m0, s45, 0xc000
	ds_read_b128 v[178:181], v195
	ds_read_b128 v[182:185], v195 offset:1024
	ds_read_b128 v[186:189], v195 offset:2048
	ds_read_b128 v[196:199], v195 offset:3072
	ds_read_b128 v[200:203], v195 offset:4096
	ds_read_b128 v[204:207], v195 offset:5120
	ds_read_b128 v[208:211], v195 offset:6144
	ds_read_b128 v[212:215], v195 offset:7168
	global_load_lds_dwordx4 v[216:217], off
	v_lshl_add_u64 v[216:217], s[28:29], 0, v[156:157]
	s_add_i32 m0, s45, 0xe000
	s_nop 0
	global_load_lds_dwordx4 v[216:217], off
	s_waitcnt vmcnt(8)
	s_waitcnt lgkmcnt(0)
	s_setprio 1
	s_barrier
	v_mfma_f32_16x16x32_bf16 v[126:129], v[130:133], v[178:181], v[126:129]
	v_mfma_f32_16x16x32_bf16 v[122:125], v[138:141], v[178:181], v[122:125]
	v_mfma_f32_16x16x32_bf16 v[118:121], v[130:133], v[186:189], v[118:121]
	v_mfma_f32_16x16x32_bf16 v[110:113], v[138:141], v[186:189], v[110:113]
	v_mfma_f32_16x16x32_bf16 v[98:101], v[130:133], v[200:203], v[98:101]
	v_mfma_f32_16x16x32_bf16 v[90:93], v[138:141], v[200:203], v[90:93]
	v_mfma_f32_16x16x32_bf16 v[82:85], v[130:133], v[208:211], v[82:85]
	v_mfma_f32_16x16x32_bf16 v[74:77], v[138:141], v[208:211], v[74:77]
	v_mfma_f32_16x16x32_bf16 v[126:129], v[134:137], v[182:185], v[126:129]
	v_mfma_f32_16x16x32_bf16 v[122:125], v[142:145], v[182:185], v[122:125]
	v_mfma_f32_16x16x32_bf16 v[118:121], v[134:137], v[196:199], v[118:121]
	v_mfma_f32_16x16x32_bf16 v[110:113], v[142:145], v[196:199], v[110:113]
	v_mfma_f32_16x16x32_bf16 v[98:101], v[134:137], v[204:207], v[98:101]
	v_mfma_f32_16x16x32_bf16 v[90:93], v[142:145], v[204:207], v[90:93]
	v_mfma_f32_16x16x32_bf16 v[82:85], v[134:137], v[212:215], v[82:85]
	v_mfma_f32_16x16x32_bf16 v[74:77], v[142:145], v[212:215], v[74:77]
	v_mfma_f32_16x16x32_bf16 v[114:117], v[162:165], v[178:181], v[114:117]
	v_mfma_f32_16x16x32_bf16 v[106:109], v[170:173], v[178:181], v[106:109]
	v_mfma_f32_16x16x32_bf16 v[102:105], v[162:165], v[186:189], v[102:105]
	v_mfma_f32_16x16x32_bf16 v[94:97], v[170:173], v[186:189], v[94:97]
	v_mfma_f32_16x16x32_bf16 v[86:89], v[162:165], v[200:203], v[86:89]
	v_mfma_f32_16x16x32_bf16 v[78:81], v[170:173], v[200:203], v[78:81]
	v_mfma_f32_16x16x32_bf16 v[70:73], v[162:165], v[208:211], v[70:73]
	v_mfma_f32_16x16x32_bf16 v[66:69], v[170:173], v[208:211], v[66:69]
	v_mfma_f32_16x16x32_bf16 v[114:117], v[166:169], v[182:185], v[114:117]
	v_mfma_f32_16x16x32_bf16 v[106:109], v[174:177], v[182:185], v[106:109]
	v_mfma_f32_16x16x32_bf16 v[102:105], v[166:169], v[196:199], v[102:105]
	v_mfma_f32_16x16x32_bf16 v[94:97], v[174:177], v[196:199], v[94:97]
	v_mfma_f32_16x16x32_bf16 v[86:89], v[166:169], v[204:207], v[86:89]
	v_mfma_f32_16x16x32_bf16 v[78:81], v[174:177], v[204:207], v[78:81]
	v_mfma_f32_16x16x32_bf16 v[70:73], v[166:169], v[212:215], v[70:73]
	v_mfma_f32_16x16x32_bf16 v[66:69], v[174:177], v[212:215], v[66:69]
	s_barrier
	s_setprio 0
	s_add_i32 s69, s58, s44
	v_lshl_add_u64 v[216:217], s[30:31], 0, v[148:149]
	s_mov_b32 m0, s69
	ds_read_b128 v[178:181], v195 offset:16384
	ds_read_b128 v[182:185], v195 offset:17408
	ds_read_b128 v[186:189], v195 offset:18432
	ds_read_b128 v[196:199], v195 offset:19456
	ds_read_b128 v[200:203], v195 offset:20480
	ds_read_b128 v[204:207], v195 offset:21504
	ds_read_b128 v[208:211], v195 offset:22528
	ds_read_b128 v[212:215], v195 offset:23552
	global_load_lds_dwordx4 v[216:217], off
	s_add_i32 m0, s69, 0x2000
	s_add_u32 s70, s30, 0x100000
	v_lshl_add_u64 v[218:219], s[30:31], 0, v[152:153]
	s_addc_u32 s71, s31, 0
	s_add_i32 s69, s59, s44
	global_load_lds_dwordx4 v[218:219], off
	v_lshl_add_u64 v[220:221], s[70:71], 0, v[148:149]
	s_mov_b32 m0, s69
	v_lshl_add_u64 v[222:223], s[34:35], 0, v[150:151]
	global_load_lds_dwordx4 v[220:221], off
	v_lshl_add_u64 v[220:221], s[70:71], 0, v[152:153]
	s_add_i32 m0, s69, 0x2000
	s_nop 0
	global_load_lds_dwordx4 v[220:221], off
	v_lshl_add_u64 v[220:221], s[34:35], 0, v[146:147]
	s_mov_b32 m0, s45
	s_nop 0
	global_load_lds_dwordx4 v[220:221], off
	s_mov_b32 m0, s46
	s_nop 0
	global_load_lds_dwordx4 v[222:223], off
	s_waitcnt vmcnt(8)
	s_waitcnt lgkmcnt(0)
	s_setprio 1
	s_barrier
	v_mfma_f32_16x16x32_bf16 v[62:65], v[130:133], v[178:181], v[62:65]
	v_mfma_f32_16x16x32_bf16 v[58:61], v[138:141], v[178:181], v[58:61]
	v_mfma_f32_16x16x32_bf16 v[46:49], v[130:133], v[186:189], v[46:49]
	v_mfma_f32_16x16x32_bf16 v[42:45], v[138:141], v[186:189], v[42:45]
	v_mfma_f32_16x16x32_bf16 v[30:33], v[130:133], v[200:203], v[30:33]
	v_mfma_f32_16x16x32_bf16 v[26:29], v[138:141], v[200:203], v[26:29]
	v_mfma_f32_16x16x32_bf16 v[14:17], v[130:133], v[208:211], v[14:17]
	v_mfma_f32_16x16x32_bf16 v[10:13], v[138:141], v[208:211], v[10:13]
	v_mfma_f32_16x16x32_bf16 v[62:65], v[134:137], v[182:185], v[62:65]
	v_mfma_f32_16x16x32_bf16 v[58:61], v[142:145], v[182:185], v[58:61]
	v_mfma_f32_16x16x32_bf16 v[46:49], v[134:137], v[196:199], v[46:49]
	v_mfma_f32_16x16x32_bf16 v[42:45], v[142:145], v[196:199], v[42:45]
	v_mfma_f32_16x16x32_bf16 v[30:33], v[134:137], v[204:207], v[30:33]
	v_mfma_f32_16x16x32_bf16 v[26:29], v[142:145], v[204:207], v[26:29]
	v_mfma_f32_16x16x32_bf16 v[14:17], v[134:137], v[212:215], v[14:17]
	v_mfma_f32_16x16x32_bf16 v[10:13], v[142:145], v[212:215], v[10:13]
	v_mfma_f32_16x16x32_bf16 v[54:57], v[162:165], v[178:181], v[54:57]
	v_mfma_f32_16x16x32_bf16 v[50:53], v[170:173], v[178:181], v[50:53]
	v_mfma_f32_16x16x32_bf16 v[38:41], v[162:165], v[186:189], v[38:41]
	v_mfma_f32_16x16x32_bf16 v[34:37], v[170:173], v[186:189], v[34:37]
	v_mfma_f32_16x16x32_bf16 v[22:25], v[162:165], v[200:203], v[22:25]
	v_mfma_f32_16x16x32_bf16 v[18:21], v[170:173], v[200:203], v[18:21]
	v_mfma_f32_16x16x32_bf16 v[6:9], v[162:165], v[208:211], v[6:9]
	v_mfma_f32_16x16x32_bf16 v[2:5], v[170:173], v[208:211], v[2:5]
	v_mfma_f32_16x16x32_bf16 v[54:57], v[166:169], v[182:185], v[54:57]
	v_mfma_f32_16x16x32_bf16 v[50:53], v[174:177], v[182:185], v[50:53]
	v_mfma_f32_16x16x32_bf16 v[38:41], v[166:169], v[196:199], v[38:41]
	v_mfma_f32_16x16x32_bf16 v[34:37], v[174:177], v[196:199], v[34:37]
	v_mfma_f32_16x16x32_bf16 v[22:25], v[166:169], v[204:207], v[22:25]
	v_mfma_f32_16x16x32_bf16 v[18:21], v[174:177], v[204:207], v[18:21]
	v_mfma_f32_16x16x32_bf16 v[6:9], v[166:169], v[212:215], v[6:9]
	v_mfma_f32_16x16x32_bf16 v[2:5], v[174:177], v[212:215], v[2:5]
	s_barrier
	s_setprio 0
	s_add_i32 s69, 0, 0x18000
	s_add_i32 s70, 0, 0x1c000
	v_add_u32_e32 v142, s69, v192
	v_add_u32_e32 v174, s70, v192
	ds_read_b128 v[130:133], v142
	ds_read_b128 v[134:137], v142 offset:1024
	ds_read_b128 v[138:141], v142 offset:2048
	ds_read_b128 v[142:145], v142 offset:3072
	ds_read_b128 v[162:165], v174
	ds_read_b128 v[166:169], v174 offset:1024
	ds_read_b128 v[170:173], v174 offset:2048
	ds_read_b128 v[174:177], v174 offset:3072
	s_add_u32 s34, s34, 0x100000
	s_addc_u32 s35, s35, 0
	s_mov_b32 m0, s47
	v_lshl_add_u64 v[224:225], s[34:35], 0, v[146:147]
	ds_read_b128 v[178:181], v195 offset:32768
	ds_read_b128 v[182:185], v195 offset:33792
	ds_read_b128 v[186:189], v195 offset:34816
	ds_read_b128 v[196:199], v195 offset:35840
	ds_read_b128 v[200:203], v195 offset:36864
	ds_read_b128 v[204:207], v195 offset:37888
	ds_read_b128 v[208:211], v195 offset:38912
	ds_read_b128 v[212:215], v195 offset:39936
	global_load_lds_dwordx4 v[224:225], off
	v_lshl_add_u64 v[224:225], s[34:35], 0, v[150:151]
	s_mov_b32 m0, s48
	s_nop 0
	global_load_lds_dwordx4 v[224:225], off
	s_waitcnt vmcnt(8)
	s_waitcnt lgkmcnt(0)
	s_setprio 1
	s_barrier
	v_mfma_f32_16x16x32_bf16 v[126:129], v[130:133], v[178:181], v[126:129]
	v_mfma_f32_16x16x32_bf16 v[122:125], v[138:141], v[178:181], v[122:125]
	v_mfma_f32_16x16x32_bf16 v[118:121], v[130:133], v[186:189], v[118:121]
	v_mfma_f32_16x16x32_bf16 v[110:113], v[138:141], v[186:189], v[110:113]
	v_mfma_f32_16x16x32_bf16 v[98:101], v[130:133], v[200:203], v[98:101]
	v_mfma_f32_16x16x32_bf16 v[90:93], v[138:141], v[200:203], v[90:93]
	v_mfma_f32_16x16x32_bf16 v[82:85], v[130:133], v[208:211], v[82:85]
	v_mfma_f32_16x16x32_bf16 v[74:77], v[138:141], v[208:211], v[74:77]
	v_mfma_f32_16x16x32_bf16 v[126:129], v[134:137], v[182:185], v[126:129]
	v_mfma_f32_16x16x32_bf16 v[122:125], v[142:145], v[182:185], v[122:125]
	v_mfma_f32_16x16x32_bf16 v[118:121], v[134:137], v[196:199], v[118:121]
	v_mfma_f32_16x16x32_bf16 v[110:113], v[142:145], v[196:199], v[110:113]
	v_mfma_f32_16x16x32_bf16 v[98:101], v[134:137], v[204:207], v[98:101]
	v_mfma_f32_16x16x32_bf16 v[90:93], v[142:145], v[204:207], v[90:93]
	v_mfma_f32_16x16x32_bf16 v[82:85], v[134:137], v[212:215], v[82:85]
	v_mfma_f32_16x16x32_bf16 v[74:77], v[142:145], v[212:215], v[74:77]
	v_mfma_f32_16x16x32_bf16 v[114:117], v[162:165], v[178:181], v[114:117]
	v_mfma_f32_16x16x32_bf16 v[106:109], v[170:173], v[178:181], v[106:109]
	v_mfma_f32_16x16x32_bf16 v[102:105], v[162:165], v[186:189], v[102:105]
	v_mfma_f32_16x16x32_bf16 v[94:97], v[170:173], v[186:189], v[94:97]
	v_mfma_f32_16x16x32_bf16 v[86:89], v[162:165], v[200:203], v[86:89]
	v_mfma_f32_16x16x32_bf16 v[78:81], v[170:173], v[200:203], v[78:81]
	v_mfma_f32_16x16x32_bf16 v[70:73], v[162:165], v[208:211], v[70:73]
	v_mfma_f32_16x16x32_bf16 v[66:69], v[170:173], v[208:211], v[66:69]
	v_mfma_f32_16x16x32_bf16 v[114:117], v[166:169], v[182:185], v[114:117]
	v_mfma_f32_16x16x32_bf16 v[106:109], v[174:177], v[182:185], v[106:109]
	v_mfma_f32_16x16x32_bf16 v[102:105], v[166:169], v[196:199], v[102:105]
	v_mfma_f32_16x16x32_bf16 v[94:97], v[174:177], v[196:199], v[94:97]
	v_mfma_f32_16x16x32_bf16 v[86:89], v[166:169], v[204:207], v[86:89]
	v_mfma_f32_16x16x32_bf16 v[78:81], v[174:177], v[204:207], v[78:81]
	v_mfma_f32_16x16x32_bf16 v[70:73], v[166:169], v[212:215], v[70:73]
	v_mfma_f32_16x16x32_bf16 v[66:69], v[174:177], v[212:215], v[66:69]
	s_barrier
	s_setprio 0
	s_add_i32 s34, s69, s44
	v_lshl_add_u64 v[216:217], v[216:217], 0, s[12:13]
	s_mov_b32 m0, s34
	ds_read_b128 v[178:181], v195 offset:49152
	ds_read_b128 v[182:185], v195 offset:50176
	ds_read_b128 v[186:189], v195 offset:51200
	ds_read_b128 v[196:199], v195 offset:52224
	ds_read_b128 v[200:203], v195 offset:53248
	ds_read_b128 v[204:207], v195 offset:54272
	ds_read_b128 v[208:211], v195 offset:55296
	ds_read_b128 v[212:215], v195 offset:56320
	global_load_lds_dwordx4 v[216:217], off
	s_add_i32 m0, s34, 0x2000
	s_add_u32 s30, s30, 0x100080
	v_lshl_add_u64 v[216:217], v[218:219], 0, s[12:13]
	s_addc_u32 s31, s31, 0
	s_add_i32 s34, s70, s44
	global_load_lds_dwordx4 v[216:217], off
	v_lshl_add_u64 v[216:217], s[30:31], 0, v[148:149]
	s_mov_b32 m0, s34
	s_nop 0
	global_load_lds_dwordx4 v[216:217], off
	v_lshl_add_u64 v[216:217], s[30:31], 0, v[152:153]
	s_add_i32 m0, s34, 0x2000
	s_nop 0
	global_load_lds_dwordx4 v[216:217], off
	v_lshl_add_u64 v[216:217], v[220:221], 0, s[12:13]
	s_mov_b32 m0, s55
	s_nop 0
	global_load_lds_dwordx4 v[216:217], off
	v_lshl_add_u64 v[216:217], v[222:223], 0, s[12:13]
	s_mov_b32 m0, s56
	s_nop 0
	global_load_lds_dwordx4 v[216:217], off
	s_waitcnt vmcnt(8)
	s_waitcnt lgkmcnt(0)
	s_setprio 1
	s_barrier
	v_mfma_f32_16x16x32_bf16 v[62:65], v[130:133], v[178:181], v[62:65]
	v_mfma_f32_16x16x32_bf16 v[58:61], v[138:141], v[178:181], v[58:61]
	v_mfma_f32_16x16x32_bf16 v[46:49], v[130:133], v[186:189], v[46:49]
	v_mfma_f32_16x16x32_bf16 v[42:45], v[138:141], v[186:189], v[42:45]
	v_mfma_f32_16x16x32_bf16 v[30:33], v[130:133], v[200:203], v[30:33]
	v_mfma_f32_16x16x32_bf16 v[26:29], v[138:141], v[200:203], v[26:29]
	v_mfma_f32_16x16x32_bf16 v[14:17], v[130:133], v[208:211], v[14:17]
	v_mfma_f32_16x16x32_bf16 v[10:13], v[138:141], v[208:211], v[10:13]
	v_mfma_f32_16x16x32_bf16 v[62:65], v[134:137], v[182:185], v[62:65]
	v_mfma_f32_16x16x32_bf16 v[58:61], v[142:145], v[182:185], v[58:61]
	v_mfma_f32_16x16x32_bf16 v[46:49], v[134:137], v[196:199], v[46:49]
	v_mfma_f32_16x16x32_bf16 v[42:45], v[142:145], v[196:199], v[42:45]
	v_mfma_f32_16x16x32_bf16 v[30:33], v[134:137], v[204:207], v[30:33]
	v_mfma_f32_16x16x32_bf16 v[26:29], v[142:145], v[204:207], v[26:29]
	v_mfma_f32_16x16x32_bf16 v[14:17], v[134:137], v[212:215], v[14:17]
	v_mfma_f32_16x16x32_bf16 v[10:13], v[142:145], v[212:215], v[10:13]
	v_mfma_f32_16x16x32_bf16 v[54:57], v[162:165], v[178:181], v[54:57]
	v_mfma_f32_16x16x32_bf16 v[50:53], v[170:173], v[178:181], v[50:53]
	v_mfma_f32_16x16x32_bf16 v[38:41], v[162:165], v[186:189], v[38:41]
	v_mfma_f32_16x16x32_bf16 v[34:37], v[170:173], v[186:189], v[34:37]
	v_mfma_f32_16x16x32_bf16 v[22:25], v[162:165], v[200:203], v[22:25]
	v_mfma_f32_16x16x32_bf16 v[18:21], v[170:173], v[200:203], v[18:21]
	v_mfma_f32_16x16x32_bf16 v[6:9], v[162:165], v[208:211], v[6:9]
	v_mfma_f32_16x16x32_bf16 v[2:5], v[170:173], v[208:211], v[2:5]
	v_mfma_f32_16x16x32_bf16 v[54:57], v[166:169], v[182:185], v[54:57]
	v_mfma_f32_16x16x32_bf16 v[50:53], v[174:177], v[182:185], v[50:53]
	v_mfma_f32_16x16x32_bf16 v[38:41], v[166:169], v[196:199], v[38:41]
	v_mfma_f32_16x16x32_bf16 v[34:37], v[174:177], v[196:199], v[34:37]
	v_mfma_f32_16x16x32_bf16 v[22:25], v[166:169], v[204:207], v[22:25]
	v_mfma_f32_16x16x32_bf16 v[18:21], v[174:177], v[204:207], v[18:21]
	v_mfma_f32_16x16x32_bf16 v[6:9], v[166:169], v[212:215], v[6:9]
	v_mfma_f32_16x16x32_bf16 v[2:5], v[174:177], v[212:215], v[2:5]
	s_barrier
	s_setprio 0
	s_add_i32 s68, s68, 2
	s_add_u32 s28, s28, 0x100
	s_addc_u32 s29, s29, 0
	s_add_u32 s63, s63, 0x100
	s_addc_u32 s65, s65, 0
	s_cmp_gt_u32 s68, 61
	s_cbranch_scc0 .LBB0_1246
	s_and_b64 vcc, exec, s[14:15]
	s_cbranch_vccz .LBB0_1249
	s_barrier

.LBB0_1521:
	ds_read_b128 v[130:133], v169
	ds_read_b128 v[134:137], v169 offset:1024
	ds_read_b128 v[138:141], v169 offset:2048
	ds_read_b128 v[142:145], v169 offset:3072
	ds_read_b128 v[162:165], v170
	ds_read_b128 v[172:175], v170 offset:1024
	ds_read_b128 v[176:179], v170 offset:2048
	ds_read_b128 v[180:183], v170 offset:3072
	s_add_u32 s38, s2, 0xfff00080
	s_addc_u32 s39, s3, -1
	s_cmp_eq_u32 s69, 60
	s_cselect_b32 s45, s29, s39
	s_cselect_b32 s44, s65, s38
	s_cselect_b32 s39, s27, s68
	s_cselect_b32 s38, s66, s67
	v_lshl_add_u64 v[216:217], s[2:3], 0, v[154:155]
	s_add_i32 m0, s37, 0xc000
	ds_read_b128 v[184:187], v171
	ds_read_b128 v[188:191], v171 offset:1024
	ds_read_b128 v[192:195], v171 offset:2048
	ds_read_b128 v[196:199], v171 offset:3072
	ds_read_b128 v[200:203], v171 offset:4096
	ds_read_b128 v[204:207], v171 offset:5120
	ds_read_b128 v[208:211], v171 offset:6144
	ds_read_b128 v[212:215], v171 offset:7168
	global_load_lds_dwordx4 v[216:217], off
	v_lshl_add_u64 v[216:217], s[2:3], 0, v[156:157]
	s_add_i32 m0, s37, 0xe000
	s_nop 0
	global_load_lds_dwordx4 v[216:217], off
	s_waitcnt vmcnt(8)
	s_waitcnt lgkmcnt(0)
	s_setprio 1
	s_barrier
	v_mfma_f32_16x16x32_bf16 v[126:129], v[130:133], v[184:187], v[126:129]
	v_mfma_f32_16x16x32_bf16 v[122:125], v[138:141], v[184:187], v[122:125]
	v_mfma_f32_16x16x32_bf16 v[114:117], v[130:133], v[192:195], v[114:117]
	v_mfma_f32_16x16x32_bf16 v[106:109], v[138:141], v[192:195], v[106:109]
	v_mfma_f32_16x16x32_bf16 v[98:101], v[130:133], v[200:203], v[98:101]
	v_mfma_f32_16x16x32_bf16 v[90:93], v[138:141], v[200:203], v[90:93]
	v_mfma_f32_16x16x32_bf16 v[82:85], v[130:133], v[208:211], v[82:85]
	v_mfma_f32_16x16x32_bf16 v[74:77], v[138:141], v[208:211], v[74:77]
	v_mfma_f32_16x16x32_bf16 v[126:129], v[134:137], v[188:191], v[126:129]
	v_mfma_f32_16x16x32_bf16 v[122:125], v[142:145], v[188:191], v[122:125]
	v_mfma_f32_16x16x32_bf16 v[114:117], v[134:137], v[196:199], v[114:117]
	v_mfma_f32_16x16x32_bf16 v[106:109], v[142:145], v[196:199], v[106:109]
	v_mfma_f32_16x16x32_bf16 v[98:101], v[134:137], v[204:207], v[98:101]
	v_mfma_f32_16x16x32_bf16 v[90:93], v[142:145], v[204:207], v[90:93]
	v_mfma_f32_16x16x32_bf16 v[82:85], v[134:137], v[212:215], v[82:85]
	v_mfma_f32_16x16x32_bf16 v[74:77], v[142:145], v[212:215], v[74:77]
	v_mfma_f32_16x16x32_bf16 v[118:121], v[162:165], v[184:187], v[118:121]
	v_mfma_f32_16x16x32_bf16 v[110:113], v[176:179], v[184:187], v[110:113]
	v_mfma_f32_16x16x32_bf16 v[102:105], v[162:165], v[192:195], v[102:105]
	v_mfma_f32_16x16x32_bf16 v[94:97], v[176:179], v[192:195], v[94:97]
	v_mfma_f32_16x16x32_bf16 v[86:89], v[162:165], v[200:203], v[86:89]
	v_mfma_f32_16x16x32_bf16 v[78:81], v[176:179], v[200:203], v[78:81]
	v_mfma_f32_16x16x32_bf16 v[70:73], v[162:165], v[208:211], v[70:73]
	v_mfma_f32_16x16x32_bf16 v[66:69], v[176:179], v[208:211], v[66:69]
	v_mfma_f32_16x16x32_bf16 v[118:121], v[172:175], v[188:191], v[118:121]
	v_mfma_f32_16x16x32_bf16 v[110:113], v[180:183], v[188:191], v[110:113]
	v_mfma_f32_16x16x32_bf16 v[102:105], v[172:175], v[196:199], v[102:105]
	v_mfma_f32_16x16x32_bf16 v[94:97], v[180:183], v[196:199], v[94:97]
	v_mfma_f32_16x16x32_bf16 v[86:89], v[172:175], v[204:207], v[86:89]
	v_mfma_f32_16x16x32_bf16 v[78:81], v[180:183], v[204:207], v[78:81]
	v_mfma_f32_16x16x32_bf16 v[70:73], v[172:175], v[212:215], v[70:73]
	v_mfma_f32_16x16x32_bf16 v[66:69], v[180:183], v[212:215], v[66:69]
	s_barrier
	s_setprio 0
	s_add_i32 s43, s57, s50
	v_lshl_add_u64 v[216:217], s[38:39], 0, v[150:151]
	s_mov_b32 m0, s43
	ds_read_b128 v[184:187], v171 offset:16384
	ds_read_b128 v[188:191], v171 offset:17408
	ds_read_b128 v[192:195], v171 offset:18432
	ds_read_b128 v[196:199], v171 offset:19456
	ds_read_b128 v[200:203], v171 offset:20480
	ds_read_b128 v[204:207], v171 offset:21504
	ds_read_b128 v[208:211], v171 offset:22528
	ds_read_b128 v[212:215], v171 offset:23552
	global_load_lds_dwordx4 v[216:217], off
	s_add_i32 m0, s43, 0x2000
	s_add_u32 s70, s38, 0x100000
	v_lshl_add_u64 v[218:219], s[38:39], 0, v[146:147]
	s_addc_u32 s71, s39, 0
	s_add_i32 s43, s58, s50
	global_load_lds_dwordx4 v[218:219], off
	v_lshl_add_u64 v[220:221], s[70:71], 0, v[150:151]
	s_mov_b32 m0, s43
	v_lshl_add_u64 v[222:223], s[44:45], 0, v[148:149]
	global_load_lds_dwordx4 v[220:221], off
	v_lshl_add_u64 v[220:221], s[70:71], 0, v[146:147]
	s_add_i32 m0, s43, 0x2000
	s_nop 0
	global_load_lds_dwordx4 v[220:221], off
	v_lshl_add_u64 v[220:221], s[44:45], 0, v[152:153]
	s_mov_b32 m0, s37
	s_nop 0
	global_load_lds_dwordx4 v[220:221], off
	s_mov_b32 m0, s51
	s_nop 0
	global_load_lds_dwordx4 v[222:223], off
	s_waitcnt vmcnt(8)
	s_waitcnt lgkmcnt(0)
	s_setprio 1
	s_barrier
	v_mfma_f32_16x16x32_bf16 v[62:65], v[130:133], v[184:187], v[62:65]
	v_mfma_f32_16x16x32_bf16 v[58:61], v[138:141], v[184:187], v[58:61]
	v_mfma_f32_16x16x32_bf16 v[50:53], v[130:133], v[192:195], v[50:53]
	v_mfma_f32_16x16x32_bf16 v[42:45], v[138:141], v[192:195], v[42:45]
	v_mfma_f32_16x16x32_bf16 v[34:37], v[130:133], v[200:203], v[34:37]
	v_mfma_f32_16x16x32_bf16 v[26:29], v[138:141], v[200:203], v[26:29]
	v_mfma_f32_16x16x32_bf16 v[18:21], v[130:133], v[208:211], v[18:21]
	v_mfma_f32_16x16x32_bf16 v[10:13], v[138:141], v[208:211], v[10:13]
	v_mfma_f32_16x16x32_bf16 v[62:65], v[134:137], v[188:191], v[62:65]
	v_mfma_f32_16x16x32_bf16 v[58:61], v[142:145], v[188:191], v[58:61]
	v_mfma_f32_16x16x32_bf16 v[50:53], v[134:137], v[196:199], v[50:53]
	v_mfma_f32_16x16x32_bf16 v[42:45], v[142:145], v[196:199], v[42:45]
	v_mfma_f32_16x16x32_bf16 v[34:37], v[134:137], v[204:207], v[34:37]
	v_mfma_f32_16x16x32_bf16 v[26:29], v[142:145], v[204:207], v[26:29]
	v_mfma_f32_16x16x32_bf16 v[18:21], v[134:137], v[212:215], v[18:21]
	v_mfma_f32_16x16x32_bf16 v[10:13], v[142:145], v[212:215], v[10:13]
	v_mfma_f32_16x16x32_bf16 v[54:57], v[162:165], v[184:187], v[54:57]
	v_mfma_f32_16x16x32_bf16 v[46:49], v[176:179], v[184:187], v[46:49]
	v_mfma_f32_16x16x32_bf16 v[38:41], v[162:165], v[192:195], v[38:41]
	v_mfma_f32_16x16x32_bf16 v[30:33], v[176:179], v[192:195], v[30:33]
	v_mfma_f32_16x16x32_bf16 v[22:25], v[162:165], v[200:203], v[22:25]
	v_mfma_f32_16x16x32_bf16 v[14:17], v[176:179], v[200:203], v[14:17]
	v_mfma_f32_16x16x32_bf16 v[6:9], v[162:165], v[208:211], v[6:9]
	v_mfma_f32_16x16x32_bf16 v[2:5], v[176:179], v[208:211], v[2:5]
	v_mfma_f32_16x16x32_bf16 v[54:57], v[172:175], v[188:191], v[54:57]
	v_mfma_f32_16x16x32_bf16 v[46:49], v[180:183], v[188:191], v[46:49]
	v_mfma_f32_16x16x32_bf16 v[38:41], v[172:175], v[196:199], v[38:41]
	v_mfma_f32_16x16x32_bf16 v[30:33], v[180:183], v[196:199], v[30:33]
	v_mfma_f32_16x16x32_bf16 v[22:25], v[172:175], v[204:207], v[22:25]
	v_mfma_f32_16x16x32_bf16 v[14:17], v[180:183], v[204:207], v[14:17]
	v_mfma_f32_16x16x32_bf16 v[6:9], v[172:175], v[212:215], v[6:9]
	v_mfma_f32_16x16x32_bf16 v[2:5], v[180:183], v[212:215], v[2:5]
	s_barrier
	s_setprio 0
	s_add_i32 s43, 0, 0x18000
	s_add_i32 s70, 0, 0x1c000
	v_add_u32_e32 v142, s43, v167
	v_add_u32_e32 v180, s70, v167
	ds_read_b128 v[130:133], v142
	ds_read_b128 v[134:137], v142 offset:1024
	ds_read_b128 v[138:141], v142 offset:2048
	ds_read_b128 v[142:145], v142 offset:3072
	ds_read_b128 v[162:165], v180
	ds_read_b128 v[172:175], v180 offset:1024
	ds_read_b128 v[176:179], v180 offset:2048
	ds_read_b128 v[180:183], v180 offset:3072
	s_add_u32 s44, s44, 0x100000
	s_addc_u32 s45, s45, 0
	s_mov_b32 m0, s52
	v_lshl_add_u64 v[224:225], s[44:45], 0, v[152:153]
	ds_read_b128 v[184:187], v171 offset:32768
	ds_read_b128 v[188:191], v171 offset:33792
	ds_read_b128 v[192:195], v171 offset:34816
	ds_read_b128 v[196:199], v171 offset:35840
	ds_read_b128 v[200:203], v171 offset:36864
	ds_read_b128 v[204:207], v171 offset:37888
	ds_read_b128 v[208:211], v171 offset:38912
	ds_read_b128 v[212:215], v171 offset:39936
	global_load_lds_dwordx4 v[224:225], off
	v_lshl_add_u64 v[224:225], s[44:45], 0, v[148:149]
	s_mov_b32 m0, s53
	s_nop 0
	global_load_lds_dwordx4 v[224:225], off
	s_waitcnt vmcnt(8)
	s_waitcnt lgkmcnt(0)
	s_setprio 1
	s_barrier
	v_mfma_f32_16x16x32_bf16 v[126:129], v[130:133], v[184:187], v[126:129]
	v_mfma_f32_16x16x32_bf16 v[122:125], v[138:141], v[184:187], v[122:125]
	v_mfma_f32_16x16x32_bf16 v[114:117], v[130:133], v[192:195], v[114:117]
	v_mfma_f32_16x16x32_bf16 v[106:109], v[138:141], v[192:195], v[106:109]
	v_mfma_f32_16x16x32_bf16 v[98:101], v[130:133], v[200:203], v[98:101]
	v_mfma_f32_16x16x32_bf16 v[90:93], v[138:141], v[200:203], v[90:93]
	v_mfma_f32_16x16x32_bf16 v[82:85], v[130:133], v[208:211], v[82:85]
	v_mfma_f32_16x16x32_bf16 v[74:77], v[138:141], v[208:211], v[74:77]
	v_mfma_f32_16x16x32_bf16 v[126:129], v[134:137], v[188:191], v[126:129]
	v_mfma_f32_16x16x32_bf16 v[122:125], v[142:145], v[188:191], v[122:125]
	v_mfma_f32_16x16x32_bf16 v[114:117], v[134:137], v[196:199], v[114:117]
	v_mfma_f32_16x16x32_bf16 v[106:109], v[142:145], v[196:199], v[106:109]
	v_mfma_f32_16x16x32_bf16 v[98:101], v[134:137], v[204:207], v[98:101]
	v_mfma_f32_16x16x32_bf16 v[90:93], v[142:145], v[204:207], v[90:93]
	v_mfma_f32_16x16x32_bf16 v[82:85], v[134:137], v[212:215], v[82:85]
	v_mfma_f32_16x16x32_bf16 v[74:77], v[142:145], v[212:215], v[74:77]
	v_mfma_f32_16x16x32_bf16 v[118:121], v[162:165], v[184:187], v[118:121]
	v_mfma_f32_16x16x32_bf16 v[110:113], v[176:179], v[184:187], v[110:113]
	v_mfma_f32_16x16x32_bf16 v[102:105], v[162:165], v[192:195], v[102:105]
	v_mfma_f32_16x16x32_bf16 v[94:97], v[176:179], v[192:195], v[94:97]
	v_mfma_f32_16x16x32_bf16 v[86:89], v[162:165], v[200:203], v[86:89]
	v_mfma_f32_16x16x32_bf16 v[78:81], v[176:179], v[200:203], v[78:81]
	v_mfma_f32_16x16x32_bf16 v[70:73], v[162:165], v[208:211], v[70:73]
	v_mfma_f32_16x16x32_bf16 v[66:69], v[176:179], v[208:211], v[66:69]
	v_mfma_f32_16x16x32_bf16 v[118:121], v[172:175], v[188:191], v[118:121]
	v_mfma_f32_16x16x32_bf16 v[110:113], v[180:183], v[188:191], v[110:113]
	v_mfma_f32_16x16x32_bf16 v[102:105], v[172:175], v[196:199], v[102:105]
	v_mfma_f32_16x16x32_bf16 v[94:97], v[180:183], v[196:199], v[94:97]
	v_mfma_f32_16x16x32_bf16 v[86:89], v[172:175], v[204:207], v[86:89]
	v_mfma_f32_16x16x32_bf16 v[78:81], v[180:183], v[204:207], v[78:81]
	v_mfma_f32_16x16x32_bf16 v[70:73], v[172:175], v[212:215], v[70:73]
	v_mfma_f32_16x16x32_bf16 v[66:69], v[180:183], v[212:215], v[66:69]
	s_barrier
	s_setprio 0
	s_add_i32 s43, s43, s50
	v_lshl_add_u64 v[216:217], v[216:217], 0, s[16:17]
	s_mov_b32 m0, s43
	ds_read_b128 v[184:187], v171 offset:49152
	ds_read_b128 v[188:191], v171 offset:50176
	ds_read_b128 v[192:195], v171 offset:51200
	ds_read_b128 v[196:199], v171 offset:52224
	ds_read_b128 v[200:203], v171 offset:53248
	ds_read_b128 v[204:207], v171 offset:54272
	ds_read_b128 v[208:211], v171 offset:55296
	ds_read_b128 v[212:215], v171 offset:56320
	global_load_lds_dwordx4 v[216:217], off
	s_add_i32 m0, s43, 0x2000
	s_add_u32 s38, s38, 0x100080
	v_lshl_add_u64 v[216:217], v[218:219], 0, s[16:17]
	s_addc_u32 s39, s39, 0
	s_add_i32 s43, s70, s50
	global_load_lds_dwordx4 v[216:217], off
	v_lshl_add_u64 v[216:217], s[38:39], 0, v[150:151]
	s_mov_b32 m0, s43
	s_nop 0
	global_load_lds_dwordx4 v[216:217], off
	v_lshl_add_u64 v[216:217], s[38:39], 0, v[146:147]
	s_add_i32 m0, s43, 0x2000
	s_nop 0
	global_load_lds_dwordx4 v[216:217], off
	v_lshl_add_u64 v[216:217], v[220:221], 0, s[16:17]
	s_mov_b32 m0, s55
	s_nop 0
	global_load_lds_dwordx4 v[216:217], off
	v_lshl_add_u64 v[216:217], v[222:223], 0, s[16:17]
	s_mov_b32 m0, s56
	s_nop 0
	global_load_lds_dwordx4 v[216:217], off
	s_waitcnt vmcnt(8)
	s_waitcnt lgkmcnt(0)
	s_setprio 1
	s_barrier
	v_mfma_f32_16x16x32_bf16 v[62:65], v[130:133], v[184:187], v[62:65]
	v_mfma_f32_16x16x32_bf16 v[58:61], v[138:141], v[184:187], v[58:61]
	v_mfma_f32_16x16x32_bf16 v[50:53], v[130:133], v[192:195], v[50:53]
	v_mfma_f32_16x16x32_bf16 v[42:45], v[138:141], v[192:195], v[42:45]
	v_mfma_f32_16x16x32_bf16 v[34:37], v[130:133], v[200:203], v[34:37]
	v_mfma_f32_16x16x32_bf16 v[26:29], v[138:141], v[200:203], v[26:29]
	v_mfma_f32_16x16x32_bf16 v[18:21], v[130:133], v[208:211], v[18:21]
	v_mfma_f32_16x16x32_bf16 v[10:13], v[138:141], v[208:211], v[10:13]
	v_mfma_f32_16x16x32_bf16 v[62:65], v[134:137], v[188:191], v[62:65]
	v_mfma_f32_16x16x32_bf16 v[58:61], v[142:145], v[188:191], v[58:61]
	v_mfma_f32_16x16x32_bf16 v[50:53], v[134:137], v[196:199], v[50:53]
	v_mfma_f32_16x16x32_bf16 v[42:45], v[142:145], v[196:199], v[42:45]
	v_mfma_f32_16x16x32_bf16 v[34:37], v[134:137], v[204:207], v[34:37]
	v_mfma_f32_16x16x32_bf16 v[26:29], v[142:145], v[204:207], v[26:29]
	v_mfma_f32_16x16x32_bf16 v[18:21], v[134:137], v[212:215], v[18:21]
	v_mfma_f32_16x16x32_bf16 v[10:13], v[142:145], v[212:215], v[10:13]
	v_mfma_f32_16x16x32_bf16 v[54:57], v[162:165], v[184:187], v[54:57]
	v_mfma_f32_16x16x32_bf16 v[46:49], v[176:179], v[184:187], v[46:49]
	v_mfma_f32_16x16x32_bf16 v[38:41], v[162:165], v[192:195], v[38:41]
	v_mfma_f32_16x16x32_bf16 v[30:33], v[176:179], v[192:195], v[30:33]
	v_mfma_f32_16x16x32_bf16 v[22:25], v[162:165], v[200:203], v[22:25]
	v_mfma_f32_16x16x32_bf16 v[14:17], v[176:179], v[200:203], v[14:17]
	v_mfma_f32_16x16x32_bf16 v[6:9], v[162:165], v[208:211], v[6:9]
	v_mfma_f32_16x16x32_bf16 v[2:5], v[176:179], v[208:211], v[2:5]
	v_mfma_f32_16x16x32_bf16 v[54:57], v[172:175], v[188:191], v[54:57]
	v_mfma_f32_16x16x32_bf16 v[46:49], v[180:183], v[188:191], v[46:49]
	v_mfma_f32_16x16x32_bf16 v[38:41], v[172:175], v[196:199], v[38:41]
	v_mfma_f32_16x16x32_bf16 v[30:33], v[180:183], v[196:199], v[30:33]
	v_mfma_f32_16x16x32_bf16 v[22:25], v[172:175], v[204:207], v[22:25]
	v_mfma_f32_16x16x32_bf16 v[14:17], v[180:183], v[204:207], v[14:17]
	v_mfma_f32_16x16x32_bf16 v[6:9], v[172:175], v[212:215], v[6:9]
	v_mfma_f32_16x16x32_bf16 v[2:5], v[180:183], v[212:215], v[2:5]
	s_barrier
	s_setprio 0
	s_add_i32 s69, s69, 2
	s_add_u32 s2, s2, 0x100
	s_addc_u32 s3, s3, 0
	s_add_u32 s67, s67, 0x100
	s_addc_u32 s68, s68, 0
	s_cmp_gt_u32 s69, 61
	s_cbranch_scc0 .LBB0_1521
	s_and_b64 vcc, exec, s[18:19]
	s_cbranch_vccz .LBB0_1524
	s_barrier

.LBB0_1697:
	ds_read_b128 v[130:133], v238
	ds_read_b128 v[134:137], v238 offset:1024
	ds_read_b128 v[138:141], v238 offset:2048
	ds_read_b128 v[142:145], v238 offset:3072
	ds_read_b128 v[146:149], v239
	ds_read_b128 v[150:153], v239 offset:1024
	ds_read_b128 v[154:157], v239 offset:2048
	ds_read_b128 v[158:161], v239 offset:3072
	s_add_u32 s56, s2, 0x100
	s_addc_u32 s57, s3, 0
	s_cmp_eq_u32 s91, 28
	s_cselect_b32 s61, s49, s57
	s_cselect_b32 s60, s87, s56
	s_cselect_b32 s59, s47, s90
	s_cselect_b32 s58, s88, s89
	v_lshl_add_u64 v[194:195], s[2:3], 0, v[210:211]
	s_add_i32 m0, s55, 0xc000
	ds_read_b128 v[162:165], v240
	ds_read_b128 v[166:169], v240 offset:1024
	ds_read_b128 v[170:173], v240 offset:2048
	ds_read_b128 v[174:177], v240 offset:3072
	ds_read_b128 v[178:181], v240 offset:4096
	ds_read_b128 v[182:185], v240 offset:5120
	ds_read_b128 v[186:189], v240 offset:6144
	ds_read_b128 v[190:193], v240 offset:7168
	global_load_lds_dwordx4 v[194:195], off
	v_lshl_add_u64 v[194:195], s[2:3], 0, v[212:213]
	s_add_i32 m0, s55, 0xe000
	s_nop 0
	global_load_lds_dwordx4 v[194:195], off
	s_waitcnt vmcnt(8)
	s_waitcnt lgkmcnt(0)
	s_setprio 1
	s_barrier
	v_mfma_i32_16x16x64_i8 v[126:129], v[130:133], v[162:165], v[126:129]
	v_mfma_i32_16x16x64_i8 v[122:125], v[138:141], v[162:165], v[122:125]
	v_mfma_i32_16x16x64_i8 v[118:121], v[130:133], v[170:173], v[118:121]
	v_mfma_i32_16x16x64_i8 v[110:113], v[138:141], v[170:173], v[110:113]
	v_mfma_i32_16x16x64_i8 v[78:81], v[130:133], v[178:181], v[78:81]
	v_mfma_i32_16x16x64_i8 v[30:33], v[138:141], v[178:181], v[30:33]
	v_mfma_i32_16x16x64_i8 v[74:77], v[130:133], v[186:189], v[74:77]
	v_mfma_i32_16x16x64_i8 v[26:29], v[138:141], v[186:189], v[26:29]
	v_mfma_i32_16x16x64_i8 v[126:129], v[134:137], v[166:169], v[126:129]
	v_mfma_i32_16x16x64_i8 v[122:125], v[142:145], v[166:169], v[122:125]
	v_mfma_i32_16x16x64_i8 v[118:121], v[134:137], v[174:177], v[118:121]
	v_mfma_i32_16x16x64_i8 v[110:113], v[142:145], v[174:177], v[110:113]
	v_mfma_i32_16x16x64_i8 v[78:81], v[134:137], v[182:185], v[78:81]
	v_mfma_i32_16x16x64_i8 v[30:33], v[142:145], v[182:185], v[30:33]
	v_mfma_i32_16x16x64_i8 v[74:77], v[134:137], v[190:193], v[74:77]
	v_mfma_i32_16x16x64_i8 v[26:29], v[142:145], v[190:193], v[26:29]
	v_mfma_i32_16x16x64_i8 v[102:105], v[146:149], v[162:165], v[102:105]
	v_mfma_i32_16x16x64_i8 v[98:101], v[154:157], v[162:165], v[98:101]
	v_mfma_i32_16x16x64_i8 v[94:97], v[146:149], v[170:173], v[94:97]
	v_mfma_i32_16x16x64_i8 v[90:93], v[154:157], v[170:173], v[90:93]
	v_mfma_i32_16x16x64_i8 v[70:73], v[146:149], v[178:181], v[70:73]
	v_mfma_i32_16x16x64_i8 v[22:25], v[154:157], v[178:181], v[22:25]
	v_mfma_i32_16x16x64_i8 v[66:69], v[146:149], v[186:189], v[66:69]
	v_mfma_i32_16x16x64_i8 v[18:21], v[154:157], v[186:189], v[18:21]
	v_mfma_i32_16x16x64_i8 v[102:105], v[150:153], v[166:169], v[102:105]
	v_mfma_i32_16x16x64_i8 v[98:101], v[158:161], v[166:169], v[98:101]
	v_mfma_i32_16x16x64_i8 v[94:97], v[150:153], v[174:177], v[94:97]
	v_mfma_i32_16x16x64_i8 v[90:93], v[158:161], v[174:177], v[90:93]
	v_mfma_i32_16x16x64_i8 v[70:73], v[150:153], v[182:185], v[70:73]
	v_mfma_i32_16x16x64_i8 v[22:25], v[158:161], v[182:185], v[22:25]
	v_mfma_i32_16x16x64_i8 v[66:69], v[150:153], v[190:193], v[66:69]
	v_mfma_i32_16x16x64_i8 v[18:21], v[158:161], v[190:193], v[18:21]
	s_barrier
	s_setprio 0
	s_add_i32 s2, s83, s66
	v_lshl_add_u64 v[194:195], s[58:59], 0, v[206:207]
	s_mov_b32 m0, s2
	ds_read_b128 v[162:165], v240 offset:16384
	ds_read_b128 v[166:169], v240 offset:17408
	ds_read_b128 v[170:173], v240 offset:18432
	ds_read_b128 v[174:177], v240 offset:19456
	ds_read_b128 v[178:181], v240 offset:20480
	ds_read_b128 v[182:185], v240 offset:21504
	ds_read_b128 v[186:189], v240 offset:22528
	ds_read_b128 v[190:193], v240 offset:23552
	global_load_lds_dwordx4 v[194:195], off
	s_add_i32 m0, s2, 0x2000
	s_add_u32 s2, s58, 0x80000
	v_lshl_add_u64 v[196:197], s[58:59], 0, v[202:203]
	s_addc_u32 s3, s59, 0
	s_add_i32 s43, s84, s66
	global_load_lds_dwordx4 v[196:197], off
	v_lshl_add_u64 v[198:199], s[2:3], 0, v[206:207]
	s_mov_b32 m0, s43
	v_lshl_add_u64 v[200:201], s[60:61], 0, v[204:205]
	global_load_lds_dwordx4 v[198:199], off
	v_lshl_add_u64 v[198:199], s[2:3], 0, v[202:203]
	s_add_i32 m0, s43, 0x2000
	s_nop 0
	global_load_lds_dwordx4 v[198:199], off
	v_lshl_add_u64 v[198:199], s[60:61], 0, v[208:209]
	s_mov_b32 m0, s55
	s_nop 0
	global_load_lds_dwordx4 v[198:199], off
	s_mov_b32 m0, s68
	s_nop 0
	global_load_lds_dwordx4 v[200:201], off
	s_waitcnt vmcnt(8)
	s_waitcnt lgkmcnt(0)
	s_setprio 1
	s_barrier
	v_mfma_i32_16x16x64_i8 v[62:65], v[130:133], v[162:165], v[62:65]
	v_mfma_i32_16x16x64_i8 v[14:17], v[138:141], v[162:165], v[14:17]
	v_mfma_i32_16x16x64_i8 v[58:61], v[130:133], v[170:173], v[58:61]
	v_mfma_i32_16x16x64_i8 v[10:13], v[138:141], v[170:173], v[10:13]
	v_mfma_i32_16x16x64_i8 v[114:117], v[130:133], v[178:181], v[114:117]
	v_mfma_i32_16x16x64_i8 v[106:109], v[138:141], v[178:181], v[106:109]
	v_mfma_i32_16x16x64_i8 v[86:89], v[130:133], v[186:189], v[86:89]
	v_mfma_i32_16x16x64_i8 v[82:85], v[138:141], v[186:189], v[82:85]
	v_mfma_i32_16x16x64_i8 v[62:65], v[134:137], v[166:169], v[62:65]
	v_mfma_i32_16x16x64_i8 v[14:17], v[142:145], v[166:169], v[14:17]
	v_mfma_i32_16x16x64_i8 v[58:61], v[134:137], v[174:177], v[58:61]
	v_mfma_i32_16x16x64_i8 v[10:13], v[142:145], v[174:177], v[10:13]
	v_mfma_i32_16x16x64_i8 v[114:117], v[134:137], v[182:185], v[114:117]
	v_mfma_i32_16x16x64_i8 v[106:109], v[142:145], v[182:185], v[106:109]
	v_mfma_i32_16x16x64_i8 v[86:89], v[134:137], v[190:193], v[86:89]
	v_mfma_i32_16x16x64_i8 v[82:85], v[142:145], v[190:193], v[82:85]
	v_mfma_i32_16x16x64_i8 v[50:53], v[146:149], v[162:165], v[50:53]
	v_mfma_i32_16x16x64_i8 v[6:9], v[154:157], v[162:165], v[6:9]
	v_mfma_i32_16x16x64_i8 v[42:45], v[146:149], v[170:173], v[42:45]
	v_mfma_i32_16x16x64_i8 v[2:5], v[154:157], v[170:173], v[2:5]
	v_mfma_i32_16x16x64_i8 v[54:57], v[146:149], v[178:181], v[54:57]
	v_mfma_i32_16x16x64_i8 v[46:49], v[154:157], v[178:181], v[46:49]
	v_mfma_i32_16x16x64_i8 v[38:41], v[146:149], v[186:189], v[38:41]
	v_mfma_i32_16x16x64_i8 v[34:37], v[154:157], v[186:189], v[34:37]
	v_mfma_i32_16x16x64_i8 v[50:53], v[150:153], v[166:169], v[50:53]
	v_mfma_i32_16x16x64_i8 v[6:9], v[158:161], v[166:169], v[6:9]
	v_mfma_i32_16x16x64_i8 v[42:45], v[150:153], v[174:177], v[42:45]
	v_mfma_i32_16x16x64_i8 v[2:5], v[158:161], v[174:177], v[2:5]
	v_mfma_i32_16x16x64_i8 v[54:57], v[150:153], v[182:185], v[54:57]
	v_mfma_i32_16x16x64_i8 v[46:49], v[158:161], v[182:185], v[46:49]
	v_mfma_i32_16x16x64_i8 v[38:41], v[150:153], v[190:193], v[38:41]
	v_mfma_i32_16x16x64_i8 v[34:37], v[158:161], v[190:193], v[34:37]
	s_barrier
	s_setprio 0
	s_add_i32 s43, 0, 0x18000
	s_add_i32 s92, 0, 0x1c000
	v_add_u32_e32 v142, s43, v237
	v_add_u32_e32 v158, s92, v237
	ds_read_b128 v[130:133], v142
	ds_read_b128 v[134:137], v142 offset:1024
	ds_read_b128 v[138:141], v142 offset:2048
	ds_read_b128 v[142:145], v142 offset:3072
	ds_read_b128 v[146:149], v158
	ds_read_b128 v[150:153], v158 offset:1024
	ds_read_b128 v[154:157], v158 offset:2048
	ds_read_b128 v[158:161], v158 offset:3072
	s_add_u32 s2, s60, 0x4000
	s_addc_u32 s3, s61, 0
	s_mov_b32 m0, s69
	v_lshl_add_u64 v[220:221], s[2:3], 0, v[208:209]
	ds_read_b128 v[162:165], v240 offset:32768
	ds_read_b128 v[166:169], v240 offset:33792
	ds_read_b128 v[170:173], v240 offset:34816
	ds_read_b128 v[174:177], v240 offset:35840
	ds_read_b128 v[178:181], v240 offset:36864
	ds_read_b128 v[182:185], v240 offset:37888
	ds_read_b128 v[186:189], v240 offset:38912
	ds_read_b128 v[190:193], v240 offset:39936
	global_load_lds_dwordx4 v[220:221], off
	v_lshl_add_u64 v[220:221], s[2:3], 0, v[204:205]
	s_mov_b32 m0, s70
	s_nop 0
	global_load_lds_dwordx4 v[220:221], off
	s_waitcnt vmcnt(8)
	s_waitcnt lgkmcnt(0)
	s_setprio 1
	s_barrier
	v_mfma_i32_16x16x64_i8 v[126:129], v[130:133], v[162:165], v[126:129]
	v_mfma_i32_16x16x64_i8 v[122:125], v[138:141], v[162:165], v[122:125]
	v_mfma_i32_16x16x64_i8 v[118:121], v[130:133], v[170:173], v[118:121]
	v_mfma_i32_16x16x64_i8 v[110:113], v[138:141], v[170:173], v[110:113]
	v_mfma_i32_16x16x64_i8 v[78:81], v[130:133], v[178:181], v[78:81]
	v_mfma_i32_16x16x64_i8 v[30:33], v[138:141], v[178:181], v[30:33]
	v_mfma_i32_16x16x64_i8 v[74:77], v[130:133], v[186:189], v[74:77]
	v_mfma_i32_16x16x64_i8 v[26:29], v[138:141], v[186:189], v[26:29]
	v_mfma_i32_16x16x64_i8 v[126:129], v[134:137], v[166:169], v[126:129]
	v_mfma_i32_16x16x64_i8 v[122:125], v[142:145], v[166:169], v[122:125]
	v_mfma_i32_16x16x64_i8 v[118:121], v[134:137], v[174:177], v[118:121]
	v_mfma_i32_16x16x64_i8 v[110:113], v[142:145], v[174:177], v[110:113]
	v_mfma_i32_16x16x64_i8 v[78:81], v[134:137], v[182:185], v[78:81]
	v_mfma_i32_16x16x64_i8 v[30:33], v[142:145], v[182:185], v[30:33]
	v_mfma_i32_16x16x64_i8 v[74:77], v[134:137], v[190:193], v[74:77]
	v_mfma_i32_16x16x64_i8 v[26:29], v[142:145], v[190:193], v[26:29]
	v_mfma_i32_16x16x64_i8 v[102:105], v[146:149], v[162:165], v[102:105]
	v_mfma_i32_16x16x64_i8 v[98:101], v[154:157], v[162:165], v[98:101]
	v_mfma_i32_16x16x64_i8 v[94:97], v[146:149], v[170:173], v[94:97]
	v_mfma_i32_16x16x64_i8 v[90:93], v[154:157], v[170:173], v[90:93]
	v_mfma_i32_16x16x64_i8 v[70:73], v[146:149], v[178:181], v[70:73]
	v_mfma_i32_16x16x64_i8 v[22:25], v[154:157], v[178:181], v[22:25]
	v_mfma_i32_16x16x64_i8 v[66:69], v[146:149], v[186:189], v[66:69]
	v_mfma_i32_16x16x64_i8 v[18:21], v[154:157], v[186:189], v[18:21]
	v_mfma_i32_16x16x64_i8 v[102:105], v[150:153], v[166:169], v[102:105]
	v_mfma_i32_16x16x64_i8 v[98:101], v[158:161], v[166:169], v[98:101]
	v_mfma_i32_16x16x64_i8 v[94:97], v[150:153], v[174:177], v[94:97]
	v_mfma_i32_16x16x64_i8 v[90:93], v[158:161], v[174:177], v[90:93]
	v_mfma_i32_16x16x64_i8 v[70:73], v[150:153], v[182:185], v[70:73]
	v_mfma_i32_16x16x64_i8 v[22:25], v[158:161], v[182:185], v[22:25]
	v_mfma_i32_16x16x64_i8 v[66:69], v[150:153], v[190:193], v[66:69]
	v_mfma_i32_16x16x64_i8 v[18:21], v[158:161], v[190:193], v[18:21]
	s_barrier
	s_setprio 0
	s_add_i32 s2, s43, s66
	v_lshl_add_u64 v[194:195], v[194:195], 0, s[36:37]
	s_mov_b32 m0, s2
	ds_read_b128 v[162:165], v240 offset:49152
	ds_read_b128 v[166:169], v240 offset:50176
	ds_read_b128 v[170:173], v240 offset:51200
	ds_read_b128 v[174:177], v240 offset:52224
	ds_read_b128 v[178:181], v240 offset:53248
	ds_read_b128 v[182:185], v240 offset:54272
	ds_read_b128 v[186:189], v240 offset:55296
	ds_read_b128 v[190:193], v240 offset:56320
	global_load_lds_dwordx4 v[194:195], off
	s_add_i32 m0, s2, 0x2000
	s_add_u32 s2, s58, 0x80080
	v_lshl_add_u64 v[194:195], v[196:197], 0, s[36:37]
	s_addc_u32 s3, s59, 0
	s_add_i32 s43, s92, s66
	global_load_lds_dwordx4 v[194:195], off
	v_lshl_add_u64 v[194:195], s[2:3], 0, v[206:207]
	s_mov_b32 m0, s43
	s_nop 0
	global_load_lds_dwordx4 v[194:195], off
	v_lshl_add_u64 v[194:195], s[2:3], 0, v[202:203]
	s_add_i32 m0, s43, 0x2000
	s_nop 0
	global_load_lds_dwordx4 v[194:195], off
	v_lshl_add_u64 v[194:195], v[198:199], 0, s[36:37]
	s_mov_b32 m0, s77
	s_nop 0
	global_load_lds_dwordx4 v[194:195], off
	v_lshl_add_u64 v[194:195], v[200:201], 0, s[36:37]
	s_mov_b32 m0, s78
	s_nop 0
	global_load_lds_dwordx4 v[194:195], off
	s_waitcnt vmcnt(8)
	s_waitcnt lgkmcnt(0)
	s_setprio 1
	s_barrier
	v_mfma_i32_16x16x64_i8 v[62:65], v[130:133], v[162:165], v[62:65]
	v_mfma_i32_16x16x64_i8 v[14:17], v[138:141], v[162:165], v[14:17]
	v_mfma_i32_16x16x64_i8 v[58:61], v[130:133], v[170:173], v[58:61]
	v_mfma_i32_16x16x64_i8 v[10:13], v[138:141], v[170:173], v[10:13]
	v_mfma_i32_16x16x64_i8 v[114:117], v[130:133], v[178:181], v[114:117]
	v_mfma_i32_16x16x64_i8 v[106:109], v[138:141], v[178:181], v[106:109]
	v_mfma_i32_16x16x64_i8 v[86:89], v[130:133], v[186:189], v[86:89]
	v_mfma_i32_16x16x64_i8 v[82:85], v[138:141], v[186:189], v[82:85]
	v_mfma_i32_16x16x64_i8 v[62:65], v[134:137], v[166:169], v[62:65]
	v_mfma_i32_16x16x64_i8 v[14:17], v[142:145], v[166:169], v[14:17]
	v_mfma_i32_16x16x64_i8 v[58:61], v[134:137], v[174:177], v[58:61]
	v_mfma_i32_16x16x64_i8 v[10:13], v[142:145], v[174:177], v[10:13]
	v_mfma_i32_16x16x64_i8 v[114:117], v[134:137], v[182:185], v[114:117]
	v_mfma_i32_16x16x64_i8 v[106:109], v[142:145], v[182:185], v[106:109]
	v_mfma_i32_16x16x64_i8 v[86:89], v[134:137], v[190:193], v[86:89]
	v_mfma_i32_16x16x64_i8 v[82:85], v[142:145], v[190:193], v[82:85]
	v_mfma_i32_16x16x64_i8 v[50:53], v[146:149], v[162:165], v[50:53]
	v_mfma_i32_16x16x64_i8 v[6:9], v[154:157], v[162:165], v[6:9]
	v_mfma_i32_16x16x64_i8 v[42:45], v[146:149], v[170:173], v[42:45]
	v_mfma_i32_16x16x64_i8 v[2:5], v[154:157], v[170:173], v[2:5]
	v_mfma_i32_16x16x64_i8 v[54:57], v[146:149], v[178:181], v[54:57]
	v_mfma_i32_16x16x64_i8 v[46:49], v[154:157], v[178:181], v[46:49]
	v_mfma_i32_16x16x64_i8 v[38:41], v[146:149], v[186:189], v[38:41]
	v_mfma_i32_16x16x64_i8 v[34:37], v[154:157], v[186:189], v[34:37]
	v_mfma_i32_16x16x64_i8 v[50:53], v[150:153], v[166:169], v[50:53]
	v_mfma_i32_16x16x64_i8 v[6:9], v[158:161], v[166:169], v[6:9]
	v_mfma_i32_16x16x64_i8 v[42:45], v[150:153], v[174:177], v[42:45]
	v_mfma_i32_16x16x64_i8 v[2:5], v[158:161], v[174:177], v[2:5]
	v_mfma_i32_16x16x64_i8 v[54:57], v[150:153], v[182:185], v[54:57]
	v_mfma_i32_16x16x64_i8 v[46:49], v[158:161], v[182:185], v[46:49]
	v_mfma_i32_16x16x64_i8 v[38:41], v[150:153], v[190:193], v[38:41]
	v_mfma_i32_16x16x64_i8 v[34:37], v[158:161], v[190:193], v[34:37]
	s_barrier
	s_setprio 0
	s_add_i32 s91, s91, 2
	s_add_u32 s89, s89, 0x100
	s_addc_u32 s90, s90, 0
	s_cmp_gt_u32 s91, 29
	s_mov_b64 s[2:3], s[56:57]
	s_cbranch_scc0 .LBB0_1697
	s_and_b64 vcc, exec, s[38:39]
	s_cbranch_vccz .LBB0_1700
	s_barrier

.LBB0_1951:
	ds_read_b128 v[130:133], v167
	ds_read_b128 v[134:137], v167 offset:1024
	ds_read_b128 v[138:141], v167 offset:2048
	ds_read_b128 v[142:145], v167 offset:3072
	ds_read_b128 v[170:173], v168
	ds_read_b128 v[174:177], v168 offset:1024
	ds_read_b128 v[178:181], v168 offset:2048
	ds_read_b128 v[182:185], v168 offset:3072
	s_add_u32 s38, s36, 0x100
	s_addc_u32 s39, s37, 0
	s_cmpk_eq_i32 s77, 0x52
	s_cselect_b32 s47, s3, s39
	s_cselect_b32 s46, s2, s38
	s_cselect_b32 s45, s35, s76
	s_cselect_b32 s44, s34, s75
	v_lshl_add_u64 v[162:163], s[36:37], 0, v[154:155]
	s_add_i32 m0, s52, 0xc000
	ds_read_b128 v[186:189], v169
	ds_read_b128 v[190:193], v169 offset:1024
	ds_read_b128 v[194:197], v169 offset:2048
	ds_read_b128 v[198:201], v169 offset:3072
	ds_read_b128 v[202:205], v169 offset:4096
	ds_read_b128 v[206:209], v169 offset:5120
	ds_read_b128 v[210:213], v169 offset:6144
	ds_read_b128 v[214:217], v169 offset:7168
	global_load_lds_dwordx4 v[162:163], off
	v_lshl_add_u64 v[162:163], s[36:37], 0, v[156:157]
	s_add_i32 m0, s52, 0xe000
	s_nop 0
	global_load_lds_dwordx4 v[162:163], off
	s_waitcnt vmcnt(8)
	s_waitcnt lgkmcnt(0)
	s_setprio 1
	s_barrier
	v_mfma_i32_16x16x64_i8 v[126:129], v[130:133], v[186:189], v[126:129]
	v_mfma_i32_16x16x64_i8 v[122:125], v[138:141], v[186:189], v[122:125]
	v_mfma_i32_16x16x64_i8 v[110:113], v[130:133], v[194:197], v[110:113]
	v_mfma_i32_16x16x64_i8 v[106:109], v[138:141], v[194:197], v[106:109]
	v_mfma_i32_16x16x64_i8 v[94:97], v[130:133], v[202:205], v[94:97]
	v_mfma_i32_16x16x64_i8 v[90:93], v[138:141], v[202:205], v[90:93]
	v_mfma_i32_16x16x64_i8 v[78:81], v[130:133], v[210:213], v[78:81]
	v_mfma_i32_16x16x64_i8 v[74:77], v[138:141], v[210:213], v[74:77]
	v_mfma_i32_16x16x64_i8 v[126:129], v[134:137], v[190:193], v[126:129]
	v_mfma_i32_16x16x64_i8 v[122:125], v[142:145], v[190:193], v[122:125]
	v_mfma_i32_16x16x64_i8 v[110:113], v[134:137], v[198:201], v[110:113]
	v_mfma_i32_16x16x64_i8 v[106:109], v[142:145], v[198:201], v[106:109]
	v_mfma_i32_16x16x64_i8 v[94:97], v[134:137], v[206:209], v[94:97]
	v_mfma_i32_16x16x64_i8 v[90:93], v[142:145], v[206:209], v[90:93]
	v_mfma_i32_16x16x64_i8 v[78:81], v[134:137], v[214:217], v[78:81]
	v_mfma_i32_16x16x64_i8 v[74:77], v[142:145], v[214:217], v[74:77]
	v_mfma_i32_16x16x64_i8 v[118:121], v[170:173], v[186:189], v[118:121]
	v_mfma_i32_16x16x64_i8 v[114:117], v[178:181], v[186:189], v[114:117]
	v_mfma_i32_16x16x64_i8 v[102:105], v[170:173], v[194:197], v[102:105]
	v_mfma_i32_16x16x64_i8 v[98:101], v[178:181], v[194:197], v[98:101]
	v_mfma_i32_16x16x64_i8 v[86:89], v[170:173], v[202:205], v[86:89]
	v_mfma_i32_16x16x64_i8 v[82:85], v[178:181], v[202:205], v[82:85]
	v_mfma_i32_16x16x64_i8 v[70:73], v[170:173], v[210:213], v[70:73]
	v_mfma_i32_16x16x64_i8 v[66:69], v[178:181], v[210:213], v[66:69]
	v_mfma_i32_16x16x64_i8 v[118:121], v[174:177], v[190:193], v[118:121]
	v_mfma_i32_16x16x64_i8 v[114:117], v[182:185], v[190:193], v[114:117]
	v_mfma_i32_16x16x64_i8 v[102:105], v[174:177], v[198:201], v[102:105]
	v_mfma_i32_16x16x64_i8 v[98:101], v[182:185], v[198:201], v[98:101]
	v_mfma_i32_16x16x64_i8 v[86:89], v[174:177], v[206:209], v[86:89]
	v_mfma_i32_16x16x64_i8 v[82:85], v[182:185], v[206:209], v[82:85]
	v_mfma_i32_16x16x64_i8 v[70:73], v[174:177], v[214:217], v[70:73]
	v_mfma_i32_16x16x64_i8 v[66:69], v[182:185], v[214:217], v[66:69]
	s_barrier
	s_setprio 0
	s_add_i32 s36, s61, s51
	v_lshl_add_u64 v[162:163], s[44:45], 0, v[150:151]
	s_mov_b32 m0, s36
	ds_read_b128 v[186:189], v169 offset:16384
	ds_read_b128 v[190:193], v169 offset:17408
	ds_read_b128 v[194:197], v169 offset:18432
	ds_read_b128 v[198:201], v169 offset:19456
	ds_read_b128 v[202:205], v169 offset:20480
	ds_read_b128 v[206:209], v169 offset:21504
	ds_read_b128 v[210:213], v169 offset:22528
	ds_read_b128 v[214:217], v169 offset:23552
	global_load_lds_dwordx4 v[162:163], off
	s_add_i32 m0, s36, 0x2000
	s_add_u32 s36, s44, 0x158000
	v_lshl_add_u64 v[218:219], s[44:45], 0, v[146:147]
	s_addc_u32 s37, s45, 0
	s_add_i32 s78, s62, s51
	global_load_lds_dwordx4 v[218:219], off
	v_lshl_add_u64 v[220:221], s[36:37], 0, v[150:151]
	s_mov_b32 m0, s78
	v_lshl_add_u64 v[222:223], s[46:47], 0, v[148:149]
	global_load_lds_dwordx4 v[220:221], off
	v_lshl_add_u64 v[220:221], s[36:37], 0, v[146:147]
	s_add_i32 m0, s78, 0x2000
	s_nop 0
	global_load_lds_dwordx4 v[220:221], off
	v_lshl_add_u64 v[220:221], s[46:47], 0, v[152:153]
	s_mov_b32 m0, s52
	s_nop 0
	global_load_lds_dwordx4 v[220:221], off
	s_mov_b32 m0, s53
	s_nop 0
	global_load_lds_dwordx4 v[222:223], off
	s_waitcnt vmcnt(8)
	s_waitcnt lgkmcnt(0)
	s_setprio 1
	s_barrier
	v_mfma_i32_16x16x64_i8 v[62:65], v[130:133], v[186:189], v[62:65]
	v_mfma_i32_16x16x64_i8 v[58:61], v[138:141], v[186:189], v[58:61]
	v_mfma_i32_16x16x64_i8 v[46:49], v[130:133], v[194:197], v[46:49]
	v_mfma_i32_16x16x64_i8 v[42:45], v[138:141], v[194:197], v[42:45]
	v_mfma_i32_16x16x64_i8 v[30:33], v[130:133], v[202:205], v[30:33]
	v_mfma_i32_16x16x64_i8 v[26:29], v[138:141], v[202:205], v[26:29]
	v_mfma_i32_16x16x64_i8 v[14:17], v[130:133], v[210:213], v[14:17]
	v_mfma_i32_16x16x64_i8 v[10:13], v[138:141], v[210:213], v[10:13]
	v_mfma_i32_16x16x64_i8 v[62:65], v[134:137], v[190:193], v[62:65]
	v_mfma_i32_16x16x64_i8 v[58:61], v[142:145], v[190:193], v[58:61]
	v_mfma_i32_16x16x64_i8 v[46:49], v[134:137], v[198:201], v[46:49]
	v_mfma_i32_16x16x64_i8 v[42:45], v[142:145], v[198:201], v[42:45]
	v_mfma_i32_16x16x64_i8 v[30:33], v[134:137], v[206:209], v[30:33]
	v_mfma_i32_16x16x64_i8 v[26:29], v[142:145], v[206:209], v[26:29]
	v_mfma_i32_16x16x64_i8 v[14:17], v[134:137], v[214:217], v[14:17]
	v_mfma_i32_16x16x64_i8 v[10:13], v[142:145], v[214:217], v[10:13]
	v_mfma_i32_16x16x64_i8 v[54:57], v[170:173], v[186:189], v[54:57]
	v_mfma_i32_16x16x64_i8 v[50:53], v[178:181], v[186:189], v[50:53]
	v_mfma_i32_16x16x64_i8 v[38:41], v[170:173], v[194:197], v[38:41]
	v_mfma_i32_16x16x64_i8 v[34:37], v[178:181], v[194:197], v[34:37]
	v_mfma_i32_16x16x64_i8 v[22:25], v[170:173], v[202:205], v[22:25]
	v_mfma_i32_16x16x64_i8 v[18:21], v[178:181], v[202:205], v[18:21]
	v_mfma_i32_16x16x64_i8 v[6:9], v[170:173], v[210:213], v[6:9]
	v_mfma_i32_16x16x64_i8 v[2:5], v[178:181], v[210:213], v[2:5]
	v_mfma_i32_16x16x64_i8 v[54:57], v[174:177], v[190:193], v[54:57]
	v_mfma_i32_16x16x64_i8 v[50:53], v[182:185], v[190:193], v[50:53]
	v_mfma_i32_16x16x64_i8 v[38:41], v[174:177], v[198:201], v[38:41]
	v_mfma_i32_16x16x64_i8 v[34:37], v[182:185], v[198:201], v[34:37]
	v_mfma_i32_16x16x64_i8 v[22:25], v[174:177], v[206:209], v[22:25]
	v_mfma_i32_16x16x64_i8 v[18:21], v[182:185], v[206:209], v[18:21]
	v_mfma_i32_16x16x64_i8 v[6:9], v[174:177], v[214:217], v[6:9]
	v_mfma_i32_16x16x64_i8 v[2:5], v[182:185], v[214:217], v[2:5]
	s_barrier
	s_setprio 0
	s_add_i32 s78, 0, 0x18000
	s_add_i32 s79, 0, 0x1c000
	v_add_u32_e32 v142, s78, v166
	v_add_u32_e32 v182, s79, v166
	ds_read_b128 v[130:133], v142
	ds_read_b128 v[134:137], v142 offset:1024
	ds_read_b128 v[138:141], v142 offset:2048
	ds_read_b128 v[142:145], v142 offset:3072
	ds_read_b128 v[170:173], v182
	ds_read_b128 v[174:177], v182 offset:1024
	ds_read_b128 v[178:181], v182 offset:2048
	ds_read_b128 v[182:185], v182 offset:3072
	s_add_u32 s36, s46, 0x158000
	s_addc_u32 s37, s47, 0
	s_mov_b32 m0, s54
	v_lshl_add_u64 v[224:225], s[36:37], 0, v[152:153]
	ds_read_b128 v[186:189], v169 offset:32768
	ds_read_b128 v[190:193], v169 offset:33792
	ds_read_b128 v[194:197], v169 offset:34816
	ds_read_b128 v[198:201], v169 offset:35840
	ds_read_b128 v[202:205], v169 offset:36864
	ds_read_b128 v[206:209], v169 offset:37888
	ds_read_b128 v[210:213], v169 offset:38912
	ds_read_b128 v[214:217], v169 offset:39936
	global_load_lds_dwordx4 v[224:225], off
	v_lshl_add_u64 v[224:225], s[36:37], 0, v[148:149]
	s_mov_b32 m0, s55
	s_nop 0
	global_load_lds_dwordx4 v[224:225], off
	s_waitcnt vmcnt(8)
	s_waitcnt lgkmcnt(0)
	s_setprio 1
	s_barrier
	v_mfma_i32_16x16x64_i8 v[126:129], v[130:133], v[186:189], v[126:129]
	v_mfma_i32_16x16x64_i8 v[122:125], v[138:141], v[186:189], v[122:125]
	v_mfma_i32_16x16x64_i8 v[110:113], v[130:133], v[194:197], v[110:113]
	v_mfma_i32_16x16x64_i8 v[106:109], v[138:141], v[194:197], v[106:109]
	v_mfma_i32_16x16x64_i8 v[94:97], v[130:133], v[202:205], v[94:97]
	v_mfma_i32_16x16x64_i8 v[90:93], v[138:141], v[202:205], v[90:93]
	v_mfma_i32_16x16x64_i8 v[78:81], v[130:133], v[210:213], v[78:81]
	v_mfma_i32_16x16x64_i8 v[74:77], v[138:141], v[210:213], v[74:77]
	v_mfma_i32_16x16x64_i8 v[126:129], v[134:137], v[190:193], v[126:129]
	v_mfma_i32_16x16x64_i8 v[122:125], v[142:145], v[190:193], v[122:125]
	v_mfma_i32_16x16x64_i8 v[110:113], v[134:137], v[198:201], v[110:113]
	v_mfma_i32_16x16x64_i8 v[106:109], v[142:145], v[198:201], v[106:109]
	v_mfma_i32_16x16x64_i8 v[94:97], v[134:137], v[206:209], v[94:97]
	v_mfma_i32_16x16x64_i8 v[90:93], v[142:145], v[206:209], v[90:93]
	v_mfma_i32_16x16x64_i8 v[78:81], v[134:137], v[214:217], v[78:81]
	v_mfma_i32_16x16x64_i8 v[74:77], v[142:145], v[214:217], v[74:77]
	v_mfma_i32_16x16x64_i8 v[118:121], v[170:173], v[186:189], v[118:121]
	v_mfma_i32_16x16x64_i8 v[114:117], v[178:181], v[186:189], v[114:117]
	v_mfma_i32_16x16x64_i8 v[102:105], v[170:173], v[194:197], v[102:105]
	v_mfma_i32_16x16x64_i8 v[98:101], v[178:181], v[194:197], v[98:101]
	v_mfma_i32_16x16x64_i8 v[86:89], v[170:173], v[202:205], v[86:89]
	v_mfma_i32_16x16x64_i8 v[82:85], v[178:181], v[202:205], v[82:85]
	v_mfma_i32_16x16x64_i8 v[70:73], v[170:173], v[210:213], v[70:73]
	v_mfma_i32_16x16x64_i8 v[66:69], v[178:181], v[210:213], v[66:69]
	v_mfma_i32_16x16x64_i8 v[118:121], v[174:177], v[190:193], v[118:121]
	v_mfma_i32_16x16x64_i8 v[114:117], v[182:185], v[190:193], v[114:117]
	v_mfma_i32_16x16x64_i8 v[102:105], v[174:177], v[198:201], v[102:105]
	v_mfma_i32_16x16x64_i8 v[98:101], v[182:185], v[198:201], v[98:101]
	v_mfma_i32_16x16x64_i8 v[86:89], v[174:177], v[206:209], v[86:89]
	v_mfma_i32_16x16x64_i8 v[82:85], v[182:185], v[206:209], v[82:85]
	v_mfma_i32_16x16x64_i8 v[70:73], v[174:177], v[214:217], v[70:73]
	v_mfma_i32_16x16x64_i8 v[66:69], v[182:185], v[214:217], v[66:69]
	s_barrier
	s_setprio 0
	s_add_i32 s36, s78, s51
	v_lshl_add_u64 v[162:163], v[162:163], 0, s[14:15]
	s_mov_b32 m0, s36
	ds_read_b128 v[186:189], v169 offset:49152
	ds_read_b128 v[190:193], v169 offset:50176
	ds_read_b128 v[194:197], v169 offset:51200
	ds_read_b128 v[198:201], v169 offset:52224
	ds_read_b128 v[202:205], v169 offset:53248
	ds_read_b128 v[206:209], v169 offset:54272
	ds_read_b128 v[210:213], v169 offset:55296
	ds_read_b128 v[214:217], v169 offset:56320
	global_load_lds_dwordx4 v[162:163], off
	s_add_i32 m0, s36, 0x2000
	s_add_u32 s36, s44, 0x158080
	v_lshl_add_u64 v[162:163], v[218:219], 0, s[14:15]
	s_addc_u32 s37, s45, 0
	s_add_i32 s44, s79, s51
	global_load_lds_dwordx4 v[162:163], off
	v_lshl_add_u64 v[162:163], s[36:37], 0, v[150:151]
	s_mov_b32 m0, s44
	s_nop 0
	global_load_lds_dwordx4 v[162:163], off
	v_lshl_add_u64 v[162:163], s[36:37], 0, v[146:147]
	s_add_i32 m0, s44, 0x2000
	s_nop 0
	global_load_lds_dwordx4 v[162:163], off
	v_lshl_add_u64 v[162:163], v[220:221], 0, s[14:15]
	s_mov_b32 m0, s59
	s_nop 0
	global_load_lds_dwordx4 v[162:163], off
	v_lshl_add_u64 v[162:163], v[222:223], 0, s[14:15]
	s_mov_b32 m0, s60
	s_nop 0
	global_load_lds_dwordx4 v[162:163], off
	s_waitcnt vmcnt(8)
	s_waitcnt lgkmcnt(0)
	s_setprio 1
	s_barrier
	v_mfma_i32_16x16x64_i8 v[62:65], v[130:133], v[186:189], v[62:65]
	v_mfma_i32_16x16x64_i8 v[58:61], v[138:141], v[186:189], v[58:61]
	v_mfma_i32_16x16x64_i8 v[46:49], v[130:133], v[194:197], v[46:49]
	v_mfma_i32_16x16x64_i8 v[42:45], v[138:141], v[194:197], v[42:45]
	v_mfma_i32_16x16x64_i8 v[30:33], v[130:133], v[202:205], v[30:33]
	v_mfma_i32_16x16x64_i8 v[26:29], v[138:141], v[202:205], v[26:29]
	v_mfma_i32_16x16x64_i8 v[14:17], v[130:133], v[210:213], v[14:17]
	v_mfma_i32_16x16x64_i8 v[10:13], v[138:141], v[210:213], v[10:13]
	v_mfma_i32_16x16x64_i8 v[62:65], v[134:137], v[190:193], v[62:65]
	v_mfma_i32_16x16x64_i8 v[58:61], v[142:145], v[190:193], v[58:61]
	v_mfma_i32_16x16x64_i8 v[46:49], v[134:137], v[198:201], v[46:49]
	v_mfma_i32_16x16x64_i8 v[42:45], v[142:145], v[198:201], v[42:45]
	v_mfma_i32_16x16x64_i8 v[30:33], v[134:137], v[206:209], v[30:33]
	v_mfma_i32_16x16x64_i8 v[26:29], v[142:145], v[206:209], v[26:29]
	v_mfma_i32_16x16x64_i8 v[14:17], v[134:137], v[214:217], v[14:17]
	v_mfma_i32_16x16x64_i8 v[10:13], v[142:145], v[214:217], v[10:13]
	v_mfma_i32_16x16x64_i8 v[54:57], v[170:173], v[186:189], v[54:57]
	v_mfma_i32_16x16x64_i8 v[50:53], v[178:181], v[186:189], v[50:53]
	v_mfma_i32_16x16x64_i8 v[38:41], v[170:173], v[194:197], v[38:41]
	v_mfma_i32_16x16x64_i8 v[34:37], v[178:181], v[194:197], v[34:37]
	v_mfma_i32_16x16x64_i8 v[22:25], v[170:173], v[202:205], v[22:25]
	v_mfma_i32_16x16x64_i8 v[18:21], v[178:181], v[202:205], v[18:21]
	v_mfma_i32_16x16x64_i8 v[6:9], v[170:173], v[210:213], v[6:9]
	v_mfma_i32_16x16x64_i8 v[2:5], v[178:181], v[210:213], v[2:5]
	v_mfma_i32_16x16x64_i8 v[54:57], v[174:177], v[190:193], v[54:57]
	v_mfma_i32_16x16x64_i8 v[50:53], v[182:185], v[190:193], v[50:53]
	v_mfma_i32_16x16x64_i8 v[38:41], v[174:177], v[198:201], v[38:41]
	v_mfma_i32_16x16x64_i8 v[34:37], v[182:185], v[198:201], v[34:37]
	v_mfma_i32_16x16x64_i8 v[22:25], v[174:177], v[206:209], v[22:25]
	v_mfma_i32_16x16x64_i8 v[18:21], v[182:185], v[206:209], v[18:21]
	v_mfma_i32_16x16x64_i8 v[6:9], v[174:177], v[214:217], v[6:9]
	v_mfma_i32_16x16x64_i8 v[2:5], v[182:185], v[214:217], v[2:5]
	s_barrier
	s_setprio 0
	s_add_i32 s77, s77, 2
	s_add_u32 s75, s75, 0x100
	s_addc_u32 s76, s76, 0
	s_cmpk_gt_u32 s77, 0x53
	s_mov_b64 s[36:37], s[38:39]
	s_cbranch_scc0 .LBB0_1951
	s_and_b64 vcc, exec, s[16:17]
	s_cbranch_vccz .LBB0_1954
	s_barrier
